# v19 + epilogue-alignment barrier behind the leading half's epilogue loads + redundant lgkmcnt(0) behind the pre-MMA barriers dropped (all bit-exact pieces stacked)
# baseline (speedup 1.0000x reference)
.Lsp_p2:
.LBB0_213:
	ds_read_b128 v[146:149], v156
	ds_read_b128 v[150:153], v156 offset:1024
	ds_read_b128 v[160:163], v156 offset:2048
	ds_read_b128 v[164:167], v156 offset:3072
	ds_read_b128 v[168:171], v157
	ds_read_b128 v[172:175], v157 offset:1024
	ds_read_b128 v[176:179], v157 offset:2048
	ds_read_b128 v[180:183], v157 offset:3072
	s_add_u32 s19, s84, 0xfff80080
	s_addc_u32 s20, s85, -1
	s_cmp_eq_u32 s18, 28
	s_cselect_b32 s89, s8, s20
	s_cselect_b32 s88, s9, s19
	s_cselect_b32 s87, s12, s17
	s_cselect_b32 s86, s13, s16
	v_lshl_add_u64 v[216:217], s[84:85], 0, v[138:139]
	s_add_i32 m0, s57, 0xc000
	ds_read_b128 v[184:187], v158
	ds_read_b128 v[188:191], v158 offset:1024
	ds_read_b128 v[192:195], v158 offset:2048
	ds_read_b128 v[196:199], v158 offset:3072
	ds_read_b128 v[200:203], v158 offset:4096
	ds_read_b128 v[204:207], v158 offset:5120
	ds_read_b128 v[208:211], v158 offset:6144
	ds_read_b128 v[212:215], v158 offset:7168
	global_load_lds_dwordx4 v[216:217], off
	v_lshl_add_u64 v[216:217], s[84:85], 0, v[140:141]
	s_add_i32 m0, s57, 0xe000
	s_nop 0
	global_load_lds_dwordx4 v[216:217], off
	s_waitcnt vmcnt(8)
	s_waitcnt lgkmcnt(0)
	s_barrier
	v_mfma_i32_16x16x64_i8 v[126:129], v[146:149], v[184:187], v[126:129]
	v_mfma_i32_16x16x64_i8 v[122:125], v[160:163], v[184:187], v[122:125]
	v_mfma_i32_16x16x64_i8 v[110:113], v[146:149], v[192:195], v[110:113]
	v_mfma_i32_16x16x64_i8 v[106:109], v[160:163], v[192:195], v[106:109]
	v_mfma_i32_16x16x64_i8 v[94:97], v[146:149], v[200:203], v[94:97]
	v_mfma_i32_16x16x64_i8 v[90:93], v[160:163], v[200:203], v[90:93]
	v_mfma_i32_16x16x64_i8 v[78:81], v[146:149], v[208:211], v[78:81]
	v_mfma_i32_16x16x64_i8 v[74:77], v[160:163], v[208:211], v[74:77]
	v_mfma_i32_16x16x64_i8 v[126:129], v[150:153], v[188:191], v[126:129]
	v_mfma_i32_16x16x64_i8 v[122:125], v[164:167], v[188:191], v[122:125]
	v_mfma_i32_16x16x64_i8 v[110:113], v[150:153], v[196:199], v[110:113]
	v_mfma_i32_16x16x64_i8 v[106:109], v[164:167], v[196:199], v[106:109]
	v_mfma_i32_16x16x64_i8 v[94:97], v[150:153], v[204:207], v[94:97]
	v_mfma_i32_16x16x64_i8 v[90:93], v[164:167], v[204:207], v[90:93]
	v_mfma_i32_16x16x64_i8 v[78:81], v[150:153], v[212:215], v[78:81]
	v_mfma_i32_16x16x64_i8 v[74:77], v[164:167], v[212:215], v[74:77]
	v_mfma_i32_16x16x64_i8 v[118:121], v[168:171], v[184:187], v[118:121]
	v_mfma_i32_16x16x64_i8 v[114:117], v[176:179], v[184:187], v[114:117]
	v_mfma_i32_16x16x64_i8 v[102:105], v[168:171], v[192:195], v[102:105]
	v_mfma_i32_16x16x64_i8 v[98:101], v[176:179], v[192:195], v[98:101]
	v_mfma_i32_16x16x64_i8 v[86:89], v[168:171], v[200:203], v[86:89]
	v_mfma_i32_16x16x64_i8 v[82:85], v[176:179], v[200:203], v[82:85]
	v_mfma_i32_16x16x64_i8 v[70:73], v[168:171], v[208:211], v[70:73]
	v_mfma_i32_16x16x64_i8 v[66:69], v[176:179], v[208:211], v[66:69]
	v_mfma_i32_16x16x64_i8 v[118:121], v[172:175], v[188:191], v[118:121]
	v_mfma_i32_16x16x64_i8 v[114:117], v[180:183], v[188:191], v[114:117]
	v_mfma_i32_16x16x64_i8 v[102:105], v[172:175], v[196:199], v[102:105]
	v_mfma_i32_16x16x64_i8 v[98:101], v[180:183], v[196:199], v[98:101]
	v_mfma_i32_16x16x64_i8 v[86:89], v[172:175], v[204:207], v[86:89]
	v_mfma_i32_16x16x64_i8 v[82:85], v[180:183], v[204:207], v[82:85]
	v_mfma_i32_16x16x64_i8 v[70:73], v[172:175], v[212:215], v[70:73]
	v_mfma_i32_16x16x64_i8 v[66:69], v[180:183], v[212:215], v[66:69]
	s_barrier
	s_add_i32 s19, s83, s35
	v_lshl_add_u64 v[216:217], s[86:87], 0, v[134:135]
	s_mov_b32 m0, s19
	ds_read_b128 v[184:187], v158 offset:16384
	ds_read_b128 v[188:191], v158 offset:17408
	ds_read_b128 v[192:195], v158 offset:18432
	ds_read_b128 v[196:199], v158 offset:19456
	ds_read_b128 v[200:203], v158 offset:20480
	ds_read_b128 v[204:207], v158 offset:21504
	ds_read_b128 v[208:211], v158 offset:22528
	ds_read_b128 v[212:215], v158 offset:23552
	global_load_lds_dwordx4 v[216:217], off
	s_add_i32 m0, s19, 0x2000
	s_add_u32 s20, s86, 0x80000
	v_lshl_add_u64 v[218:219], s[86:87], 0, v[130:131]
	s_addc_u32 s21, s87, 0
	s_add_i32 s19, s90, s35
	global_load_lds_dwordx4 v[218:219], off
	v_lshl_add_u64 v[220:221], s[20:21], 0, v[134:135]
	s_mov_b32 m0, s19
	v_lshl_add_u64 v[222:223], s[88:89], 0, v[132:133]
	global_load_lds_dwordx4 v[220:221], off
	v_lshl_add_u64 v[220:221], s[20:21], 0, v[130:131]
	s_add_i32 m0, s19, 0x2000
	s_nop 0
	global_load_lds_dwordx4 v[220:221], off
	v_lshl_add_u64 v[220:221], s[88:89], 0, v[136:137]
	s_mov_b32 m0, s57
	s_nop 0
	global_load_lds_dwordx4 v[220:221], off
	s_mov_b32 m0, s58
	s_nop 0
	global_load_lds_dwordx4 v[222:223], off
	s_waitcnt vmcnt(8)
	s_waitcnt lgkmcnt(0)
	s_barrier
	v_mfma_i32_16x16x64_i8 v[62:65], v[146:149], v[184:187], v[62:65]
	v_mfma_i32_16x16x64_i8 v[58:61], v[160:163], v[184:187], v[58:61]
	v_mfma_i32_16x16x64_i8 v[46:49], v[146:149], v[192:195], v[46:49]
	v_mfma_i32_16x16x64_i8 v[42:45], v[160:163], v[192:195], v[42:45]
	v_mfma_i32_16x16x64_i8 v[30:33], v[146:149], v[200:203], v[30:33]
	v_mfma_i32_16x16x64_i8 v[26:29], v[160:163], v[200:203], v[26:29]
	v_mfma_i32_16x16x64_i8 v[14:17], v[146:149], v[208:211], v[14:17]
	v_mfma_i32_16x16x64_i8 v[10:13], v[160:163], v[208:211], v[10:13]
	v_mfma_i32_16x16x64_i8 v[62:65], v[150:153], v[188:191], v[62:65]
	v_mfma_i32_16x16x64_i8 v[58:61], v[164:167], v[188:191], v[58:61]
	v_mfma_i32_16x16x64_i8 v[46:49], v[150:153], v[196:199], v[46:49]
	v_mfma_i32_16x16x64_i8 v[42:45], v[164:167], v[196:199], v[42:45]
	v_mfma_i32_16x16x64_i8 v[30:33], v[150:153], v[204:207], v[30:33]
	v_mfma_i32_16x16x64_i8 v[26:29], v[164:167], v[204:207], v[26:29]
	v_mfma_i32_16x16x64_i8 v[14:17], v[150:153], v[212:215], v[14:17]
	v_mfma_i32_16x16x64_i8 v[10:13], v[164:167], v[212:215], v[10:13]
	v_mfma_i32_16x16x64_i8 v[54:57], v[168:171], v[184:187], v[54:57]
	v_mfma_i32_16x16x64_i8 v[50:53], v[176:179], v[184:187], v[50:53]
	v_mfma_i32_16x16x64_i8 v[38:41], v[168:171], v[192:195], v[38:41]
	v_mfma_i32_16x16x64_i8 v[34:37], v[176:179], v[192:195], v[34:37]
	v_mfma_i32_16x16x64_i8 v[22:25], v[168:171], v[200:203], v[22:25]
	v_mfma_i32_16x16x64_i8 v[18:21], v[176:179], v[200:203], v[18:21]
	v_mfma_i32_16x16x64_i8 v[6:9], v[168:171], v[208:211], v[6:9]
	v_mfma_i32_16x16x64_i8 v[2:5], v[176:179], v[208:211], v[2:5]
	v_mfma_i32_16x16x64_i8 v[54:57], v[172:175], v[188:191], v[54:57]
	v_mfma_i32_16x16x64_i8 v[50:53], v[180:183], v[188:191], v[50:53]
	v_mfma_i32_16x16x64_i8 v[38:41], v[172:175], v[196:199], v[38:41]
	v_mfma_i32_16x16x64_i8 v[34:37], v[180:183], v[196:199], v[34:37]
	v_mfma_i32_16x16x64_i8 v[22:25], v[172:175], v[204:207], v[22:25]
	v_mfma_i32_16x16x64_i8 v[18:21], v[180:183], v[204:207], v[18:21]
	v_mfma_i32_16x16x64_i8 v[6:9], v[172:175], v[212:215], v[6:9]
	v_mfma_i32_16x16x64_i8 v[2:5], v[180:183], v[212:215], v[2:5]
	s_barrier
	s_add_i32 s19, 0, 0x18000
	v_add_u32_e32 v159, s19, v154
	s_add_i32 s22, 0, 0x1c000
	ds_read_b128 v[146:149], v159
	ds_read_b128 v[150:153], v159 offset:1024
	ds_read_b128 v[160:163], v159 offset:2048
	ds_read_b128 v[164:167], v159 offset:3072
	v_add_u32_e32 v159, s22, v154
	ds_read_b128 v[168:171], v159
	ds_read_b128 v[172:175], v159 offset:1024
	ds_read_b128 v[176:179], v159 offset:2048
	ds_read_b128 v[180:183], v159 offset:3072
	s_add_u32 s20, s88, 0x80000
	s_addc_u32 s21, s89, 0
	s_mov_b32 m0, s59
	v_lshl_add_u64 v[224:225], s[20:21], 0, v[136:137]
	ds_read_b128 v[184:187], v158 offset:32768
	ds_read_b128 v[188:191], v158 offset:33792
	ds_read_b128 v[192:195], v158 offset:34816
	ds_read_b128 v[196:199], v158 offset:35840
	ds_read_b128 v[200:203], v158 offset:36864
	ds_read_b128 v[204:207], v158 offset:37888
	ds_read_b128 v[208:211], v158 offset:38912
	ds_read_b128 v[212:215], v158 offset:39936
	global_load_lds_dwordx4 v[224:225], off
	v_lshl_add_u64 v[224:225], s[20:21], 0, v[132:133]
	s_mov_b32 m0, s61
	s_nop 0
	global_load_lds_dwordx4 v[224:225], off
	s_waitcnt vmcnt(8)
	s_waitcnt lgkmcnt(0)
	s_barrier
	v_mfma_i32_16x16x64_i8 v[126:129], v[146:149], v[184:187], v[126:129]
	v_mfma_i32_16x16x64_i8 v[122:125], v[160:163], v[184:187], v[122:125]
	v_mfma_i32_16x16x64_i8 v[110:113], v[146:149], v[192:195], v[110:113]
	v_mfma_i32_16x16x64_i8 v[106:109], v[160:163], v[192:195], v[106:109]
	v_mfma_i32_16x16x64_i8 v[94:97], v[146:149], v[200:203], v[94:97]
	v_mfma_i32_16x16x64_i8 v[90:93], v[160:163], v[200:203], v[90:93]
	v_mfma_i32_16x16x64_i8 v[78:81], v[146:149], v[208:211], v[78:81]
	v_mfma_i32_16x16x64_i8 v[74:77], v[160:163], v[208:211], v[74:77]
	v_mfma_i32_16x16x64_i8 v[126:129], v[150:153], v[188:191], v[126:129]
	v_mfma_i32_16x16x64_i8 v[122:125], v[164:167], v[188:191], v[122:125]
	v_mfma_i32_16x16x64_i8 v[110:113], v[150:153], v[196:199], v[110:113]
	v_mfma_i32_16x16x64_i8 v[106:109], v[164:167], v[196:199], v[106:109]
	v_mfma_i32_16x16x64_i8 v[94:97], v[150:153], v[204:207], v[94:97]
	v_mfma_i32_16x16x64_i8 v[90:93], v[164:167], v[204:207], v[90:93]
	v_mfma_i32_16x16x64_i8 v[78:81], v[150:153], v[212:215], v[78:81]
	v_mfma_i32_16x16x64_i8 v[74:77], v[164:167], v[212:215], v[74:77]
	v_mfma_i32_16x16x64_i8 v[118:121], v[168:171], v[184:187], v[118:121]
	v_mfma_i32_16x16x64_i8 v[114:117], v[176:179], v[184:187], v[114:117]
	v_mfma_i32_16x16x64_i8 v[102:105], v[168:171], v[192:195], v[102:105]
	v_mfma_i32_16x16x64_i8 v[98:101], v[176:179], v[192:195], v[98:101]
	v_mfma_i32_16x16x64_i8 v[86:89], v[168:171], v[200:203], v[86:89]
	v_mfma_i32_16x16x64_i8 v[82:85], v[176:179], v[200:203], v[82:85]
	v_mfma_i32_16x16x64_i8 v[70:73], v[168:171], v[208:211], v[70:73]
	v_mfma_i32_16x16x64_i8 v[66:69], v[176:179], v[208:211], v[66:69]
	v_mfma_i32_16x16x64_i8 v[118:121], v[172:175], v[188:191], v[118:121]
	v_mfma_i32_16x16x64_i8 v[114:117], v[180:183], v[188:191], v[114:117]
	v_mfma_i32_16x16x64_i8 v[102:105], v[172:175], v[196:199], v[102:105]
	v_mfma_i32_16x16x64_i8 v[98:101], v[180:183], v[196:199], v[98:101]
	v_mfma_i32_16x16x64_i8 v[86:89], v[172:175], v[204:207], v[86:89]
	v_mfma_i32_16x16x64_i8 v[82:85], v[180:183], v[204:207], v[82:85]
	v_mfma_i32_16x16x64_i8 v[70:73], v[172:175], v[212:215], v[70:73]
	v_mfma_i32_16x16x64_i8 v[66:69], v[180:183], v[212:215], v[66:69]
	s_barrier
	s_add_i32 s19, s19, s35
	v_lshl_add_u64 v[216:217], v[216:217], 0, s[4:5]
	s_mov_b32 m0, s19
	ds_read_b128 v[184:187], v158 offset:49152
	ds_read_b128 v[188:191], v158 offset:50176
	ds_read_b128 v[192:195], v158 offset:51200
	ds_read_b128 v[196:199], v158 offset:52224
	ds_read_b128 v[200:203], v158 offset:53248
	ds_read_b128 v[204:207], v158 offset:54272
	ds_read_b128 v[208:211], v158 offset:55296
	ds_read_b128 v[212:215], v158 offset:56320
	global_load_lds_dwordx4 v[216:217], off
	s_add_i32 m0, s19, 0x2000
	s_add_u32 s20, s86, 0x80080
	v_lshl_add_u64 v[216:217], v[218:219], 0, s[4:5]
	s_addc_u32 s21, s87, 0
	s_add_i32 s19, s22, s35
	global_load_lds_dwordx4 v[216:217], off
	v_lshl_add_u64 v[216:217], s[20:21], 0, v[134:135]
	s_mov_b32 m0, s19
	s_nop 0
	global_load_lds_dwordx4 v[216:217], off
	v_lshl_add_u64 v[216:217], s[20:21], 0, v[130:131]
	s_add_i32 m0, s19, 0x2000
	s_nop 0
	global_load_lds_dwordx4 v[216:217], off
	v_lshl_add_u64 v[216:217], v[220:221], 0, s[4:5]
	s_mov_b32 m0, s67
	s_nop 0
	global_load_lds_dwordx4 v[216:217], off
	v_lshl_add_u64 v[216:217], v[222:223], 0, s[4:5]
	s_mov_b32 m0, s68
	s_nop 0
	global_load_lds_dwordx4 v[216:217], off
	s_waitcnt vmcnt(8)
	s_waitcnt lgkmcnt(0)
	s_barrier
	v_mfma_i32_16x16x64_i8 v[62:65], v[146:149], v[184:187], v[62:65]
	v_mfma_i32_16x16x64_i8 v[58:61], v[160:163], v[184:187], v[58:61]
	v_mfma_i32_16x16x64_i8 v[46:49], v[146:149], v[192:195], v[46:49]
	v_mfma_i32_16x16x64_i8 v[42:45], v[160:163], v[192:195], v[42:45]
	v_mfma_i32_16x16x64_i8 v[30:33], v[146:149], v[200:203], v[30:33]
	v_mfma_i32_16x16x64_i8 v[26:29], v[160:163], v[200:203], v[26:29]
	v_mfma_i32_16x16x64_i8 v[14:17], v[146:149], v[208:211], v[14:17]
	v_mfma_i32_16x16x64_i8 v[10:13], v[160:163], v[208:211], v[10:13]
	v_mfma_i32_16x16x64_i8 v[62:65], v[150:153], v[188:191], v[62:65]
	v_mfma_i32_16x16x64_i8 v[58:61], v[164:167], v[188:191], v[58:61]
	v_mfma_i32_16x16x64_i8 v[46:49], v[150:153], v[196:199], v[46:49]
	v_mfma_i32_16x16x64_i8 v[42:45], v[164:167], v[196:199], v[42:45]
	v_mfma_i32_16x16x64_i8 v[30:33], v[150:153], v[204:207], v[30:33]
	v_mfma_i32_16x16x64_i8 v[26:29], v[164:167], v[204:207], v[26:29]
	v_mfma_i32_16x16x64_i8 v[14:17], v[150:153], v[212:215], v[14:17]
	v_mfma_i32_16x16x64_i8 v[10:13], v[164:167], v[212:215], v[10:13]
	v_mfma_i32_16x16x64_i8 v[54:57], v[168:171], v[184:187], v[54:57]
	v_mfma_i32_16x16x64_i8 v[50:53], v[176:179], v[184:187], v[50:53]
	v_mfma_i32_16x16x64_i8 v[38:41], v[168:171], v[192:195], v[38:41]
	v_mfma_i32_16x16x64_i8 v[34:37], v[176:179], v[192:195], v[34:37]
	v_mfma_i32_16x16x64_i8 v[22:25], v[168:171], v[200:203], v[22:25]
	v_mfma_i32_16x16x64_i8 v[18:21], v[176:179], v[200:203], v[18:21]
	v_mfma_i32_16x16x64_i8 v[6:9], v[168:171], v[208:211], v[6:9]
	v_mfma_i32_16x16x64_i8 v[2:5], v[176:179], v[208:211], v[2:5]
	v_mfma_i32_16x16x64_i8 v[54:57], v[172:175], v[188:191], v[54:57]
	v_mfma_i32_16x16x64_i8 v[50:53], v[180:183], v[188:191], v[50:53]
	v_mfma_i32_16x16x64_i8 v[38:41], v[172:175], v[196:199], v[38:41]
	v_mfma_i32_16x16x64_i8 v[34:37], v[180:183], v[196:199], v[34:37]
	v_mfma_i32_16x16x64_i8 v[22:25], v[172:175], v[204:207], v[22:25]
	v_mfma_i32_16x16x64_i8 v[18:21], v[180:183], v[204:207], v[18:21]
	v_mfma_i32_16x16x64_i8 v[6:9], v[172:175], v[212:215], v[6:9]
	v_mfma_i32_16x16x64_i8 v[2:5], v[180:183], v[212:215], v[2:5]
	s_barrier
	s_add_i32 s18, s18, 2
	s_add_u32 s84, s84, 0x100
	s_addc_u32 s85, s85, 0
	s_add_u32 s16, s16, 0x100
	s_addc_u32 s17, s17, 0
	s_cmp_gt_u32 s18, 29
	s_cbranch_scc0 .LBB0_213
	s_setprio 0
	s_and_b64 vcc, exec, s[6:7]
	s_cbranch_vccz .LBB0_216

.Lsp_p3:
.LBB0_362:
	ds_read_b128 v[106:109], v168
	ds_read_b128 v[110:113], v168 offset:1024
	ds_read_b128 v[114:117], v168 offset:2048
	ds_read_b128 v[122:125], v168 offset:3072
	ds_read_b128 v[160:163], v169
	ds_read_b128 v[172:175], v169 offset:1024
	ds_read_b128 v[176:179], v169 offset:2048
	ds_read_b128 v[180:183], v169 offset:3072
	s_add_u32 s16, s6, 0xffea8080
	s_addc_u32 s17, s7, -1
	s_cmpk_eq_i32 s13, 0x52
	s_cselect_b32 s85, s51, s17
	s_cselect_b32 s84, s50, s16
	s_cselect_b32 s83, s81, s12
	s_cselect_b32 s82, s80, s8
	v_lshl_add_u64 v[216:217], s[6:7], 0, v[154:155]
	s_add_i32 m0, s56, 0xc000
	ds_read_b128 v[184:187], v170
	ds_read_b128 v[188:191], v170 offset:1024
	ds_read_b128 v[192:195], v170 offset:2048
	ds_read_b128 v[196:199], v170 offset:3072
	ds_read_b128 v[200:203], v170 offset:4096
	ds_read_b128 v[204:207], v170 offset:5120
	ds_read_b128 v[208:211], v170 offset:6144
	ds_read_b128 v[212:215], v170 offset:7168
	global_load_lds_dwordx4 v[216:217], off
	v_lshl_add_u64 v[216:217], s[6:7], 0, v[156:157]
	s_add_i32 m0, s56, 0xe000
	s_nop 0
	global_load_lds_dwordx4 v[216:217], off
	s_waitcnt vmcnt(8)
	s_waitcnt lgkmcnt(0)
	s_barrier
	v_mfma_i32_16x16x64_i8 v[142:145], v[106:109], v[184:187], v[142:145]
	v_mfma_i32_16x16x64_i8 v[138:141], v[114:117], v[184:187], v[138:141]
	v_mfma_i32_16x16x64_i8 v[126:129], v[106:109], v[192:195], v[126:129]
	v_mfma_i32_16x16x64_i8 v[118:121], v[114:117], v[192:195], v[118:121]
	v_mfma_i32_16x16x64_i8 v[94:97], v[106:109], v[200:203], v[94:97]
	v_mfma_i32_16x16x64_i8 v[90:93], v[114:117], v[200:203], v[90:93]
	v_mfma_i32_16x16x64_i8 v[78:81], v[106:109], v[208:211], v[78:81]
	v_mfma_i32_16x16x64_i8 v[74:77], v[114:117], v[208:211], v[74:77]
	v_mfma_i32_16x16x64_i8 v[142:145], v[110:113], v[188:191], v[142:145]
	v_mfma_i32_16x16x64_i8 v[138:141], v[122:125], v[188:191], v[138:141]
	v_mfma_i32_16x16x64_i8 v[126:129], v[110:113], v[196:199], v[126:129]
	v_mfma_i32_16x16x64_i8 v[118:121], v[122:125], v[196:199], v[118:121]
	v_mfma_i32_16x16x64_i8 v[94:97], v[110:113], v[204:207], v[94:97]
	v_mfma_i32_16x16x64_i8 v[90:93], v[122:125], v[204:207], v[90:93]
	v_mfma_i32_16x16x64_i8 v[78:81], v[110:113], v[212:215], v[78:81]
	v_mfma_i32_16x16x64_i8 v[74:77], v[122:125], v[212:215], v[74:77]
	v_mfma_i32_16x16x64_i8 v[134:137], v[160:163], v[184:187], v[134:137]
	v_mfma_i32_16x16x64_i8 v[130:133], v[176:179], v[184:187], v[130:133]
	v_mfma_i32_16x16x64_i8 v[102:105], v[160:163], v[192:195], v[102:105]
	v_mfma_i32_16x16x64_i8 v[98:101], v[176:179], v[192:195], v[98:101]
	v_mfma_i32_16x16x64_i8 v[86:89], v[160:163], v[200:203], v[86:89]
	v_mfma_i32_16x16x64_i8 v[82:85], v[176:179], v[200:203], v[82:85]
	v_mfma_i32_16x16x64_i8 v[70:73], v[160:163], v[208:211], v[70:73]
	v_mfma_i32_16x16x64_i8 v[66:69], v[176:179], v[208:211], v[66:69]
	v_mfma_i32_16x16x64_i8 v[134:137], v[172:175], v[188:191], v[134:137]
	v_mfma_i32_16x16x64_i8 v[130:133], v[180:183], v[188:191], v[130:133]
	v_mfma_i32_16x16x64_i8 v[102:105], v[172:175], v[196:199], v[102:105]
	v_mfma_i32_16x16x64_i8 v[98:101], v[180:183], v[196:199], v[98:101]
	v_mfma_i32_16x16x64_i8 v[86:89], v[172:175], v[204:207], v[86:89]
	v_mfma_i32_16x16x64_i8 v[82:85], v[180:183], v[204:207], v[82:85]
	v_mfma_i32_16x16x64_i8 v[70:73], v[172:175], v[212:215], v[70:73]
	v_mfma_i32_16x16x64_i8 v[66:69], v[180:183], v[212:215], v[66:69]
	s_barrier
	s_add_i32 s16, s87, s35
	v_lshl_add_u64 v[216:217], s[82:83], 0, v[148:149]
	s_mov_b32 m0, s16
	ds_read_b128 v[184:187], v170 offset:16384
	ds_read_b128 v[188:191], v170 offset:17408
	ds_read_b128 v[192:195], v170 offset:18432
	ds_read_b128 v[196:199], v170 offset:19456
	ds_read_b128 v[200:203], v170 offset:20480
	ds_read_b128 v[204:207], v170 offset:21504
	ds_read_b128 v[208:211], v170 offset:22528
	ds_read_b128 v[212:215], v170 offset:23552
	global_load_lds_dwordx4 v[216:217], off
	s_add_i32 m0, s16, 0x2000
	s_add_u32 s16, s82, 0x158000
	v_lshl_add_u64 v[218:219], s[82:83], 0, v[152:153]
	s_addc_u32 s17, s83, 0
	s_add_i32 s18, s88, s35
	global_load_lds_dwordx4 v[218:219], off
	v_lshl_add_u64 v[220:221], s[16:17], 0, v[148:149]
	s_mov_b32 m0, s18
	v_lshl_add_u64 v[222:223], s[84:85], 0, v[150:151]
	global_load_lds_dwordx4 v[220:221], off
	v_lshl_add_u64 v[220:221], s[16:17], 0, v[152:153]
	s_add_i32 m0, s18, 0x2000
	s_nop 0
	global_load_lds_dwordx4 v[220:221], off
	v_lshl_add_u64 v[220:221], s[84:85], 0, v[146:147]
	s_mov_b32 m0, s56
	s_nop 0
	global_load_lds_dwordx4 v[220:221], off
	s_mov_b32 m0, s57
	s_nop 0
	global_load_lds_dwordx4 v[222:223], off
	s_waitcnt vmcnt(8)
	s_waitcnt lgkmcnt(0)
	s_barrier
	v_mfma_i32_16x16x64_i8 v[62:65], v[106:109], v[184:187], v[62:65]
	v_mfma_i32_16x16x64_i8 v[58:61], v[114:117], v[184:187], v[58:61]
	v_mfma_i32_16x16x64_i8 v[46:49], v[106:109], v[192:195], v[46:49]
	v_mfma_i32_16x16x64_i8 v[42:45], v[114:117], v[192:195], v[42:45]
	v_mfma_i32_16x16x64_i8 v[30:33], v[106:109], v[200:203], v[30:33]
	v_mfma_i32_16x16x64_i8 v[26:29], v[114:117], v[200:203], v[26:29]
	v_mfma_i32_16x16x64_i8 v[14:17], v[106:109], v[208:211], v[14:17]
	v_mfma_i32_16x16x64_i8 v[10:13], v[114:117], v[208:211], v[10:13]
	v_mfma_i32_16x16x64_i8 v[62:65], v[110:113], v[188:191], v[62:65]
	v_mfma_i32_16x16x64_i8 v[58:61], v[122:125], v[188:191], v[58:61]
	v_mfma_i32_16x16x64_i8 v[46:49], v[110:113], v[196:199], v[46:49]
	v_mfma_i32_16x16x64_i8 v[42:45], v[122:125], v[196:199], v[42:45]
	v_mfma_i32_16x16x64_i8 v[30:33], v[110:113], v[204:207], v[30:33]
	v_mfma_i32_16x16x64_i8 v[26:29], v[122:125], v[204:207], v[26:29]
	v_mfma_i32_16x16x64_i8 v[14:17], v[110:113], v[212:215], v[14:17]
	v_mfma_i32_16x16x64_i8 v[10:13], v[122:125], v[212:215], v[10:13]
	v_mfma_i32_16x16x64_i8 v[54:57], v[160:163], v[184:187], v[54:57]
	v_mfma_i32_16x16x64_i8 v[50:53], v[176:179], v[184:187], v[50:53]
	v_mfma_i32_16x16x64_i8 v[38:41], v[160:163], v[192:195], v[38:41]
	v_mfma_i32_16x16x64_i8 v[34:37], v[176:179], v[192:195], v[34:37]
	v_mfma_i32_16x16x64_i8 v[22:25], v[160:163], v[200:203], v[22:25]
	v_mfma_i32_16x16x64_i8 v[18:21], v[176:179], v[200:203], v[18:21]
	v_mfma_i32_16x16x64_i8 v[6:9], v[160:163], v[208:211], v[6:9]
	v_mfma_i32_16x16x64_i8 v[2:5], v[176:179], v[208:211], v[2:5]
	v_mfma_i32_16x16x64_i8 v[54:57], v[172:175], v[188:191], v[54:57]
	v_mfma_i32_16x16x64_i8 v[50:53], v[180:183], v[188:191], v[50:53]
	v_mfma_i32_16x16x64_i8 v[38:41], v[172:175], v[196:199], v[38:41]
	v_mfma_i32_16x16x64_i8 v[34:37], v[180:183], v[196:199], v[34:37]
	v_mfma_i32_16x16x64_i8 v[22:25], v[172:175], v[204:207], v[22:25]
	v_mfma_i32_16x16x64_i8 v[18:21], v[180:183], v[204:207], v[18:21]
	v_mfma_i32_16x16x64_i8 v[6:9], v[172:175], v[212:215], v[6:9]
	v_mfma_i32_16x16x64_i8 v[2:5], v[180:183], v[212:215], v[2:5]
	s_barrier
	s_add_i32 s18, 0, 0x18000
	s_add_i32 s19, 0, 0x1c000
	v_add_u32_e32 v122, s18, v165
	v_add_u32_e32 v164, s19, v165
	ds_read_b128 v[106:109], v122
	ds_read_b128 v[110:113], v122 offset:1024
	ds_read_b128 v[114:117], v122 offset:2048
	ds_read_b128 v[122:125], v122 offset:3072
	ds_read_b128 v[160:163], v164
	ds_read_b128 v[172:175], v164 offset:1024
	ds_read_b128 v[176:179], v164 offset:2048
	ds_read_b128 v[180:183], v164 offset:3072
	s_add_u32 s16, s84, 0x158000
	s_addc_u32 s17, s85, 0
	s_mov_b32 m0, s58
	v_lshl_add_u64 v[224:225], s[16:17], 0, v[146:147]
	ds_read_b128 v[184:187], v170 offset:32768
	ds_read_b128 v[188:191], v170 offset:33792
	ds_read_b128 v[192:195], v170 offset:34816
	ds_read_b128 v[196:199], v170 offset:35840
	ds_read_b128 v[200:203], v170 offset:36864
	ds_read_b128 v[204:207], v170 offset:37888
	ds_read_b128 v[208:211], v170 offset:38912
	ds_read_b128 v[212:215], v170 offset:39936
	global_load_lds_dwordx4 v[224:225], off
	v_lshl_add_u64 v[224:225], s[16:17], 0, v[150:151]
	s_mov_b32 m0, s59
	s_nop 0
	global_load_lds_dwordx4 v[224:225], off
	s_waitcnt vmcnt(8)
	s_waitcnt lgkmcnt(0)
	s_barrier
	v_mfma_i32_16x16x64_i8 v[142:145], v[106:109], v[184:187], v[142:145]
	v_mfma_i32_16x16x64_i8 v[138:141], v[114:117], v[184:187], v[138:141]
	v_mfma_i32_16x16x64_i8 v[126:129], v[106:109], v[192:195], v[126:129]
	v_mfma_i32_16x16x64_i8 v[118:121], v[114:117], v[192:195], v[118:121]
	v_mfma_i32_16x16x64_i8 v[94:97], v[106:109], v[200:203], v[94:97]
	v_mfma_i32_16x16x64_i8 v[90:93], v[114:117], v[200:203], v[90:93]
	v_mfma_i32_16x16x64_i8 v[78:81], v[106:109], v[208:211], v[78:81]
	v_mfma_i32_16x16x64_i8 v[74:77], v[114:117], v[208:211], v[74:77]
	v_mfma_i32_16x16x64_i8 v[142:145], v[110:113], v[188:191], v[142:145]
	v_mfma_i32_16x16x64_i8 v[138:141], v[122:125], v[188:191], v[138:141]
	v_mfma_i32_16x16x64_i8 v[126:129], v[110:113], v[196:199], v[126:129]
	v_mfma_i32_16x16x64_i8 v[118:121], v[122:125], v[196:199], v[118:121]
	v_mfma_i32_16x16x64_i8 v[94:97], v[110:113], v[204:207], v[94:97]
	v_mfma_i32_16x16x64_i8 v[90:93], v[122:125], v[204:207], v[90:93]
	v_mfma_i32_16x16x64_i8 v[78:81], v[110:113], v[212:215], v[78:81]
	v_mfma_i32_16x16x64_i8 v[74:77], v[122:125], v[212:215], v[74:77]
	v_mfma_i32_16x16x64_i8 v[134:137], v[160:163], v[184:187], v[134:137]
	v_mfma_i32_16x16x64_i8 v[130:133], v[176:179], v[184:187], v[130:133]
	v_mfma_i32_16x16x64_i8 v[102:105], v[160:163], v[192:195], v[102:105]
	v_mfma_i32_16x16x64_i8 v[98:101], v[176:179], v[192:195], v[98:101]
	v_mfma_i32_16x16x64_i8 v[86:89], v[160:163], v[200:203], v[86:89]
	v_mfma_i32_16x16x64_i8 v[82:85], v[176:179], v[200:203], v[82:85]
	v_mfma_i32_16x16x64_i8 v[70:73], v[160:163], v[208:211], v[70:73]
	v_mfma_i32_16x16x64_i8 v[66:69], v[176:179], v[208:211], v[66:69]
	v_mfma_i32_16x16x64_i8 v[134:137], v[172:175], v[188:191], v[134:137]
	v_mfma_i32_16x16x64_i8 v[130:133], v[180:183], v[188:191], v[130:133]
	v_mfma_i32_16x16x64_i8 v[102:105], v[172:175], v[196:199], v[102:105]
	v_mfma_i32_16x16x64_i8 v[98:101], v[180:183], v[196:199], v[98:101]
	v_mfma_i32_16x16x64_i8 v[86:89], v[172:175], v[204:207], v[86:89]
	v_mfma_i32_16x16x64_i8 v[82:85], v[180:183], v[204:207], v[82:85]
	v_mfma_i32_16x16x64_i8 v[70:73], v[172:175], v[212:215], v[70:73]
	v_mfma_i32_16x16x64_i8 v[66:69], v[180:183], v[212:215], v[66:69]
	s_barrier
	s_add_i32 s16, s18, s35
	v_lshl_add_u64 v[216:217], v[216:217], 0, s[44:45]
	s_mov_b32 m0, s16
	ds_read_b128 v[184:187], v170 offset:49152
	ds_read_b128 v[188:191], v170 offset:50176
	ds_read_b128 v[192:195], v170 offset:51200
	ds_read_b128 v[196:199], v170 offset:52224
	ds_read_b128 v[200:203], v170 offset:53248
	ds_read_b128 v[204:207], v170 offset:54272
	ds_read_b128 v[208:211], v170 offset:55296
	ds_read_b128 v[212:215], v170 offset:56320
	global_load_lds_dwordx4 v[216:217], off
	s_add_i32 m0, s16, 0x2000
	s_add_u32 s16, s82, 0x158080
	v_lshl_add_u64 v[216:217], v[218:219], 0, s[44:45]
	s_addc_u32 s17, s83, 0
	s_add_i32 s18, s19, s35
	global_load_lds_dwordx4 v[216:217], off
	v_lshl_add_u64 v[216:217], s[16:17], 0, v[148:149]
	s_mov_b32 m0, s18
	s_nop 0
	global_load_lds_dwordx4 v[216:217], off
	v_lshl_add_u64 v[216:217], s[16:17], 0, v[152:153]
	s_add_i32 m0, s18, 0x2000
	s_nop 0
	global_load_lds_dwordx4 v[216:217], off
	v_lshl_add_u64 v[216:217], v[220:221], 0, s[44:45]
	s_mov_b32 m0, s61
	s_nop 0
	global_load_lds_dwordx4 v[216:217], off
	v_lshl_add_u64 v[216:217], v[222:223], 0, s[44:45]
	s_mov_b32 m0, s66
	s_nop 0
	global_load_lds_dwordx4 v[216:217], off
	s_waitcnt vmcnt(8)
	s_waitcnt lgkmcnt(0)
	s_barrier
	v_mfma_i32_16x16x64_i8 v[62:65], v[106:109], v[184:187], v[62:65]
	v_mfma_i32_16x16x64_i8 v[58:61], v[114:117], v[184:187], v[58:61]
	v_mfma_i32_16x16x64_i8 v[46:49], v[106:109], v[192:195], v[46:49]
	v_mfma_i32_16x16x64_i8 v[42:45], v[114:117], v[192:195], v[42:45]
	v_mfma_i32_16x16x64_i8 v[30:33], v[106:109], v[200:203], v[30:33]
	v_mfma_i32_16x16x64_i8 v[26:29], v[114:117], v[200:203], v[26:29]
	v_mfma_i32_16x16x64_i8 v[14:17], v[106:109], v[208:211], v[14:17]
	v_mfma_i32_16x16x64_i8 v[10:13], v[114:117], v[208:211], v[10:13]
	v_mfma_i32_16x16x64_i8 v[62:65], v[110:113], v[188:191], v[62:65]
	v_mfma_i32_16x16x64_i8 v[58:61], v[122:125], v[188:191], v[58:61]
	v_mfma_i32_16x16x64_i8 v[46:49], v[110:113], v[196:199], v[46:49]
	v_mfma_i32_16x16x64_i8 v[42:45], v[122:125], v[196:199], v[42:45]
	v_mfma_i32_16x16x64_i8 v[30:33], v[110:113], v[204:207], v[30:33]
	v_mfma_i32_16x16x64_i8 v[26:29], v[122:125], v[204:207], v[26:29]
	v_mfma_i32_16x16x64_i8 v[14:17], v[110:113], v[212:215], v[14:17]
	v_mfma_i32_16x16x64_i8 v[10:13], v[122:125], v[212:215], v[10:13]
	v_mfma_i32_16x16x64_i8 v[54:57], v[160:163], v[184:187], v[54:57]
	v_mfma_i32_16x16x64_i8 v[50:53], v[176:179], v[184:187], v[50:53]
	v_mfma_i32_16x16x64_i8 v[38:41], v[160:163], v[192:195], v[38:41]
	v_mfma_i32_16x16x64_i8 v[34:37], v[176:179], v[192:195], v[34:37]
	v_mfma_i32_16x16x64_i8 v[22:25], v[160:163], v[200:203], v[22:25]
	v_mfma_i32_16x16x64_i8 v[18:21], v[176:179], v[200:203], v[18:21]
	v_mfma_i32_16x16x64_i8 v[6:9], v[160:163], v[208:211], v[6:9]
	v_mfma_i32_16x16x64_i8 v[2:5], v[176:179], v[208:211], v[2:5]
	v_mfma_i32_16x16x64_i8 v[54:57], v[172:175], v[188:191], v[54:57]
	v_mfma_i32_16x16x64_i8 v[50:53], v[180:183], v[188:191], v[50:53]
	v_mfma_i32_16x16x64_i8 v[38:41], v[172:175], v[196:199], v[38:41]
	v_mfma_i32_16x16x64_i8 v[34:37], v[180:183], v[196:199], v[34:37]
	v_mfma_i32_16x16x64_i8 v[22:25], v[172:175], v[204:207], v[22:25]
	v_mfma_i32_16x16x64_i8 v[18:21], v[180:183], v[204:207], v[18:21]
	v_mfma_i32_16x16x64_i8 v[6:9], v[172:175], v[212:215], v[6:9]
	v_mfma_i32_16x16x64_i8 v[2:5], v[180:183], v[212:215], v[2:5]
	s_barrier
	s_add_i32 s13, s13, 2
	s_add_u32 s6, s6, 0x100
	s_addc_u32 s7, s7, 0
	s_add_u32 s8, s8, 0x100
	s_addc_u32 s12, s12, 0
	s_cmpk_gt_u32 s13, 0x53
	s_cbranch_scc0 .LBB0_362
	s_setprio 0
	s_and_b64 vcc, exec, s[46:47]
	s_cbranch_vccz .LBB0_365

.Lsp_p5:
.LBB0_541:
	ds_read_b128 v[146:149], v154
	ds_read_b128 v[158:161], v154 offset:1024
	ds_read_b128 v[162:165], v154 offset:2048
	ds_read_b128 v[166:169], v154 offset:3072
	ds_read_b128 v[170:173], v155
	ds_read_b128 v[174:177], v155 offset:1024
	ds_read_b128 v[178:181], v155 offset:2048
	ds_read_b128 v[182:185], v155 offset:3072
	s_add_u32 s18, s84, 0xfff00080
	s_addc_u32 s19, s85, -1
	s_cmp_eq_u32 s17, 60
	s_cselect_b32 s89, s5, s19
	s_cselect_b32 s88, s8, s18
	s_cselect_b32 s87, s9, s16
	s_cselect_b32 s86, s12, s13
	v_lshl_add_u64 v[218:219], s[84:85], 0, v[138:139]
	s_add_i32 m0, s56, 0xc000
	ds_read_b128 v[186:189], v156
	ds_read_b128 v[190:193], v156 offset:1024
	ds_read_b128 v[194:197], v156 offset:2048
	ds_read_b128 v[198:201], v156 offset:3072
	ds_read_b128 v[202:205], v156 offset:4096
	ds_read_b128 v[206:209], v156 offset:5120
	ds_read_b128 v[210:213], v156 offset:6144
	ds_read_b128 v[214:217], v156 offset:7168
	global_load_lds_dwordx4 v[218:219], off
	v_lshl_add_u64 v[218:219], s[84:85], 0, v[140:141]
	s_add_i32 m0, s56, 0xe000
	s_nop 0
	global_load_lds_dwordx4 v[218:219], off
	s_waitcnt vmcnt(8)
	s_waitcnt lgkmcnt(0)
	s_barrier
	v_mfma_f32_16x16x32_bf16 v[126:129], v[146:149], v[186:189], v[126:129]
	v_mfma_f32_16x16x32_bf16 v[122:125], v[162:165], v[186:189], v[122:125]
	v_mfma_f32_16x16x32_bf16 v[110:113], v[146:149], v[194:197], v[110:113]
	v_mfma_f32_16x16x32_bf16 v[106:109], v[162:165], v[194:197], v[106:109]
	v_mfma_f32_16x16x32_bf16 v[94:97], v[146:149], v[202:205], v[94:97]
	v_mfma_f32_16x16x32_bf16 v[90:93], v[162:165], v[202:205], v[90:93]
	v_mfma_f32_16x16x32_bf16 v[78:81], v[146:149], v[210:213], v[78:81]
	v_mfma_f32_16x16x32_bf16 v[74:77], v[162:165], v[210:213], v[74:77]
	v_mfma_f32_16x16x32_bf16 v[126:129], v[158:161], v[190:193], v[126:129]
	v_mfma_f32_16x16x32_bf16 v[122:125], v[166:169], v[190:193], v[122:125]
	v_mfma_f32_16x16x32_bf16 v[110:113], v[158:161], v[198:201], v[110:113]
	v_mfma_f32_16x16x32_bf16 v[106:109], v[166:169], v[198:201], v[106:109]
	v_mfma_f32_16x16x32_bf16 v[94:97], v[158:161], v[206:209], v[94:97]
	v_mfma_f32_16x16x32_bf16 v[90:93], v[166:169], v[206:209], v[90:93]
	v_mfma_f32_16x16x32_bf16 v[78:81], v[158:161], v[214:217], v[78:81]
	v_mfma_f32_16x16x32_bf16 v[74:77], v[166:169], v[214:217], v[74:77]
	v_mfma_f32_16x16x32_bf16 v[118:121], v[170:173], v[186:189], v[118:121]
	v_mfma_f32_16x16x32_bf16 v[114:117], v[178:181], v[186:189], v[114:117]
	v_mfma_f32_16x16x32_bf16 v[102:105], v[170:173], v[194:197], v[102:105]
	v_mfma_f32_16x16x32_bf16 v[98:101], v[178:181], v[194:197], v[98:101]
	v_mfma_f32_16x16x32_bf16 v[86:89], v[170:173], v[202:205], v[86:89]
	v_mfma_f32_16x16x32_bf16 v[82:85], v[178:181], v[202:205], v[82:85]
	v_mfma_f32_16x16x32_bf16 v[70:73], v[170:173], v[210:213], v[70:73]
	v_mfma_f32_16x16x32_bf16 v[66:69], v[178:181], v[210:213], v[66:69]
	v_mfma_f32_16x16x32_bf16 v[118:121], v[174:177], v[190:193], v[118:121]
	v_mfma_f32_16x16x32_bf16 v[114:117], v[182:185], v[190:193], v[114:117]
	v_mfma_f32_16x16x32_bf16 v[102:105], v[174:177], v[198:201], v[102:105]
	v_mfma_f32_16x16x32_bf16 v[98:101], v[182:185], v[198:201], v[98:101]
	v_mfma_f32_16x16x32_bf16 v[86:89], v[174:177], v[206:209], v[86:89]
	v_mfma_f32_16x16x32_bf16 v[82:85], v[182:185], v[206:209], v[82:85]
	v_mfma_f32_16x16x32_bf16 v[70:73], v[174:177], v[214:217], v[70:73]
	v_mfma_f32_16x16x32_bf16 v[66:69], v[182:185], v[214:217], v[66:69]
	s_barrier
	s_add_i32 s18, s83, s35
	v_lshl_add_u64 v[218:219], s[86:87], 0, v[132:133]
	s_mov_b32 m0, s18
	ds_read_b128 v[186:189], v156 offset:16384
	ds_read_b128 v[190:193], v156 offset:17408
	ds_read_b128 v[194:197], v156 offset:18432
	ds_read_b128 v[198:201], v156 offset:19456
	ds_read_b128 v[202:205], v156 offset:20480
	ds_read_b128 v[206:209], v156 offset:21504
	ds_read_b128 v[210:213], v156 offset:22528
	ds_read_b128 v[214:217], v156 offset:23552
	global_load_lds_dwordx4 v[218:219], off
	s_add_i32 m0, s18, 0x2000
	s_add_u32 s18, s86, 0x100000
	v_lshl_add_u64 v[220:221], s[86:87], 0, v[136:137]
	s_addc_u32 s19, s87, 0
	s_add_i32 s20, s90, s35
	global_load_lds_dwordx4 v[220:221], off
	v_lshl_add_u64 v[222:223], s[18:19], 0, v[132:133]
	s_mov_b32 m0, s20
	v_lshl_add_u64 v[224:225], s[88:89], 0, v[134:135]
	global_load_lds_dwordx4 v[222:223], off
	v_lshl_add_u64 v[222:223], s[18:19], 0, v[136:137]
	s_add_i32 m0, s20, 0x2000
	s_nop 0
	global_load_lds_dwordx4 v[222:223], off
	v_lshl_add_u64 v[222:223], s[88:89], 0, v[130:131]
	s_mov_b32 m0, s56
	s_nop 0
	global_load_lds_dwordx4 v[222:223], off
	s_mov_b32 m0, s57
	s_nop 0
	global_load_lds_dwordx4 v[224:225], off
	s_waitcnt vmcnt(8)
	s_waitcnt lgkmcnt(0)
	s_barrier
	v_mfma_f32_16x16x32_bf16 v[62:65], v[146:149], v[186:189], v[62:65]
	v_mfma_f32_16x16x32_bf16 v[58:61], v[162:165], v[186:189], v[58:61]
	v_mfma_f32_16x16x32_bf16 v[46:49], v[146:149], v[194:197], v[46:49]
	v_mfma_f32_16x16x32_bf16 v[42:45], v[162:165], v[194:197], v[42:45]
	v_mfma_f32_16x16x32_bf16 v[30:33], v[146:149], v[202:205], v[30:33]
	v_mfma_f32_16x16x32_bf16 v[26:29], v[162:165], v[202:205], v[26:29]
	v_mfma_f32_16x16x32_bf16 v[14:17], v[146:149], v[210:213], v[14:17]
	v_mfma_f32_16x16x32_bf16 v[10:13], v[162:165], v[210:213], v[10:13]
	v_mfma_f32_16x16x32_bf16 v[62:65], v[158:161], v[190:193], v[62:65]
	v_mfma_f32_16x16x32_bf16 v[58:61], v[166:169], v[190:193], v[58:61]
	v_mfma_f32_16x16x32_bf16 v[46:49], v[158:161], v[198:201], v[46:49]
	v_mfma_f32_16x16x32_bf16 v[42:45], v[166:169], v[198:201], v[42:45]
	v_mfma_f32_16x16x32_bf16 v[30:33], v[158:161], v[206:209], v[30:33]
	v_mfma_f32_16x16x32_bf16 v[26:29], v[166:169], v[206:209], v[26:29]
	v_mfma_f32_16x16x32_bf16 v[14:17], v[158:161], v[214:217], v[14:17]
	v_mfma_f32_16x16x32_bf16 v[10:13], v[166:169], v[214:217], v[10:13]
	v_mfma_f32_16x16x32_bf16 v[54:57], v[170:173], v[186:189], v[54:57]
	v_mfma_f32_16x16x32_bf16 v[50:53], v[178:181], v[186:189], v[50:53]
	v_mfma_f32_16x16x32_bf16 v[38:41], v[170:173], v[194:197], v[38:41]
	v_mfma_f32_16x16x32_bf16 v[34:37], v[178:181], v[194:197], v[34:37]
	v_mfma_f32_16x16x32_bf16 v[22:25], v[170:173], v[202:205], v[22:25]
	v_mfma_f32_16x16x32_bf16 v[18:21], v[178:181], v[202:205], v[18:21]
	v_mfma_f32_16x16x32_bf16 v[6:9], v[170:173], v[210:213], v[6:9]
	v_mfma_f32_16x16x32_bf16 v[2:5], v[178:181], v[210:213], v[2:5]
	v_mfma_f32_16x16x32_bf16 v[54:57], v[174:177], v[190:193], v[54:57]
	v_mfma_f32_16x16x32_bf16 v[50:53], v[182:185], v[190:193], v[50:53]
	v_mfma_f32_16x16x32_bf16 v[38:41], v[174:177], v[198:201], v[38:41]
	v_mfma_f32_16x16x32_bf16 v[34:37], v[182:185], v[198:201], v[34:37]
	v_mfma_f32_16x16x32_bf16 v[22:25], v[174:177], v[206:209], v[22:25]
	v_mfma_f32_16x16x32_bf16 v[18:21], v[182:185], v[206:209], v[18:21]
	v_mfma_f32_16x16x32_bf16 v[6:9], v[174:177], v[214:217], v[6:9]
	v_mfma_f32_16x16x32_bf16 v[2:5], v[182:185], v[214:217], v[2:5]
	s_barrier
	s_add_i32 s20, 0, 0x18000
	v_add_u32_e32 v150, s20, v151
	s_add_i32 s21, 0, 0x1c000
	ds_read_b128 v[146:149], v150
	ds_read_b128 v[158:161], v150 offset:1024
	ds_read_b128 v[162:165], v150 offset:2048
	ds_read_b128 v[166:169], v150 offset:3072
	v_add_u32_e32 v150, s21, v151
	ds_read_b128 v[170:173], v150
	ds_read_b128 v[174:177], v150 offset:1024
	ds_read_b128 v[178:181], v150 offset:2048
	ds_read_b128 v[182:185], v150 offset:3072
	s_add_u32 s18, s88, 0x100000
	s_addc_u32 s19, s89, 0
	s_mov_b32 m0, s58
	v_lshl_add_u64 v[228:229], s[18:19], 0, v[130:131]
	ds_read_b128 v[186:189], v156 offset:32768
	ds_read_b128 v[190:193], v156 offset:33792
	ds_read_b128 v[194:197], v156 offset:34816
	ds_read_b128 v[198:201], v156 offset:35840
	ds_read_b128 v[202:205], v156 offset:36864
	ds_read_b128 v[206:209], v156 offset:37888
	ds_read_b128 v[210:213], v156 offset:38912
	ds_read_b128 v[214:217], v156 offset:39936
	global_load_lds_dwordx4 v[228:229], off
	v_lshl_add_u64 v[228:229], s[18:19], 0, v[134:135]
	s_mov_b32 m0, s59
	s_nop 0
	global_load_lds_dwordx4 v[228:229], off
	s_waitcnt vmcnt(8)
	s_waitcnt lgkmcnt(0)
	s_barrier
	v_mfma_f32_16x16x32_bf16 v[126:129], v[146:149], v[186:189], v[126:129]
	v_mfma_f32_16x16x32_bf16 v[122:125], v[162:165], v[186:189], v[122:125]
	v_mfma_f32_16x16x32_bf16 v[110:113], v[146:149], v[194:197], v[110:113]
	v_mfma_f32_16x16x32_bf16 v[106:109], v[162:165], v[194:197], v[106:109]
	v_mfma_f32_16x16x32_bf16 v[94:97], v[146:149], v[202:205], v[94:97]
	v_mfma_f32_16x16x32_bf16 v[90:93], v[162:165], v[202:205], v[90:93]
	v_mfma_f32_16x16x32_bf16 v[78:81], v[146:149], v[210:213], v[78:81]
	v_mfma_f32_16x16x32_bf16 v[74:77], v[162:165], v[210:213], v[74:77]
	v_mfma_f32_16x16x32_bf16 v[126:129], v[158:161], v[190:193], v[126:129]
	v_mfma_f32_16x16x32_bf16 v[122:125], v[166:169], v[190:193], v[122:125]
	v_mfma_f32_16x16x32_bf16 v[110:113], v[158:161], v[198:201], v[110:113]
	v_mfma_f32_16x16x32_bf16 v[106:109], v[166:169], v[198:201], v[106:109]
	v_mfma_f32_16x16x32_bf16 v[94:97], v[158:161], v[206:209], v[94:97]
	v_mfma_f32_16x16x32_bf16 v[90:93], v[166:169], v[206:209], v[90:93]
	v_mfma_f32_16x16x32_bf16 v[78:81], v[158:161], v[214:217], v[78:81]
	v_mfma_f32_16x16x32_bf16 v[74:77], v[166:169], v[214:217], v[74:77]
	v_mfma_f32_16x16x32_bf16 v[118:121], v[170:173], v[186:189], v[118:121]
	v_mfma_f32_16x16x32_bf16 v[114:117], v[178:181], v[186:189], v[114:117]
	v_mfma_f32_16x16x32_bf16 v[102:105], v[170:173], v[194:197], v[102:105]
	v_mfma_f32_16x16x32_bf16 v[98:101], v[178:181], v[194:197], v[98:101]
	v_mfma_f32_16x16x32_bf16 v[86:89], v[170:173], v[202:205], v[86:89]
	v_mfma_f32_16x16x32_bf16 v[82:85], v[178:181], v[202:205], v[82:85]
	v_mfma_f32_16x16x32_bf16 v[70:73], v[170:173], v[210:213], v[70:73]
	v_mfma_f32_16x16x32_bf16 v[66:69], v[178:181], v[210:213], v[66:69]
	v_mfma_f32_16x16x32_bf16 v[118:121], v[174:177], v[190:193], v[118:121]
	v_mfma_f32_16x16x32_bf16 v[114:117], v[182:185], v[190:193], v[114:117]
	v_mfma_f32_16x16x32_bf16 v[102:105], v[174:177], v[198:201], v[102:105]
	v_mfma_f32_16x16x32_bf16 v[98:101], v[182:185], v[198:201], v[98:101]
	v_mfma_f32_16x16x32_bf16 v[86:89], v[174:177], v[206:209], v[86:89]
	v_mfma_f32_16x16x32_bf16 v[82:85], v[182:185], v[206:209], v[82:85]
	v_mfma_f32_16x16x32_bf16 v[70:73], v[174:177], v[214:217], v[70:73]
	v_mfma_f32_16x16x32_bf16 v[66:69], v[182:185], v[214:217], v[66:69]
	s_barrier
	s_add_i32 s18, s20, s35
	v_lshl_add_u64 v[218:219], v[218:219], 0, s[40:41]
	s_mov_b32 m0, s18
	ds_read_b128 v[186:189], v156 offset:49152
	ds_read_b128 v[190:193], v156 offset:50176
	ds_read_b128 v[194:197], v156 offset:51200
	ds_read_b128 v[198:201], v156 offset:52224
	ds_read_b128 v[202:205], v156 offset:53248
	ds_read_b128 v[206:209], v156 offset:54272
	ds_read_b128 v[210:213], v156 offset:55296
	ds_read_b128 v[214:217], v156 offset:56320
	global_load_lds_dwordx4 v[218:219], off
	s_add_i32 m0, s18, 0x2000
	s_add_u32 s18, s86, 0x100080
	v_lshl_add_u64 v[218:219], v[220:221], 0, s[40:41]
	s_addc_u32 s19, s87, 0
	s_add_i32 s20, s21, s35
	global_load_lds_dwordx4 v[218:219], off
	v_lshl_add_u64 v[218:219], s[18:19], 0, v[132:133]
	s_mov_b32 m0, s20
	s_nop 0
	global_load_lds_dwordx4 v[218:219], off
	v_lshl_add_u64 v[218:219], s[18:19], 0, v[136:137]
	s_add_i32 m0, s20, 0x2000
	s_nop 0
	global_load_lds_dwordx4 v[218:219], off
	v_lshl_add_u64 v[218:219], v[222:223], 0, s[40:41]
	s_mov_b32 m0, s66
	s_nop 0
	global_load_lds_dwordx4 v[218:219], off
	v_lshl_add_u64 v[218:219], v[224:225], 0, s[40:41]
	s_mov_b32 m0, s67
	s_nop 0
	global_load_lds_dwordx4 v[218:219], off
	s_waitcnt vmcnt(8)
	s_waitcnt lgkmcnt(0)
	s_barrier
	v_mfma_f32_16x16x32_bf16 v[62:65], v[146:149], v[186:189], v[62:65]
	v_mfma_f32_16x16x32_bf16 v[58:61], v[162:165], v[186:189], v[58:61]
	v_mfma_f32_16x16x32_bf16 v[46:49], v[146:149], v[194:197], v[46:49]
	v_mfma_f32_16x16x32_bf16 v[42:45], v[162:165], v[194:197], v[42:45]
	v_mfma_f32_16x16x32_bf16 v[30:33], v[146:149], v[202:205], v[30:33]
	v_mfma_f32_16x16x32_bf16 v[26:29], v[162:165], v[202:205], v[26:29]
	v_mfma_f32_16x16x32_bf16 v[14:17], v[146:149], v[210:213], v[14:17]
	v_mfma_f32_16x16x32_bf16 v[10:13], v[162:165], v[210:213], v[10:13]
	v_mfma_f32_16x16x32_bf16 v[62:65], v[158:161], v[190:193], v[62:65]
	v_mfma_f32_16x16x32_bf16 v[58:61], v[166:169], v[190:193], v[58:61]
	v_mfma_f32_16x16x32_bf16 v[46:49], v[158:161], v[198:201], v[46:49]
	v_mfma_f32_16x16x32_bf16 v[42:45], v[166:169], v[198:201], v[42:45]
	v_mfma_f32_16x16x32_bf16 v[30:33], v[158:161], v[206:209], v[30:33]
	v_mfma_f32_16x16x32_bf16 v[26:29], v[166:169], v[206:209], v[26:29]
	v_mfma_f32_16x16x32_bf16 v[14:17], v[158:161], v[214:217], v[14:17]
	v_mfma_f32_16x16x32_bf16 v[10:13], v[166:169], v[214:217], v[10:13]
	v_mfma_f32_16x16x32_bf16 v[54:57], v[170:173], v[186:189], v[54:57]
	v_mfma_f32_16x16x32_bf16 v[50:53], v[178:181], v[186:189], v[50:53]
	v_mfma_f32_16x16x32_bf16 v[38:41], v[170:173], v[194:197], v[38:41]
	v_mfma_f32_16x16x32_bf16 v[34:37], v[178:181], v[194:197], v[34:37]
	v_mfma_f32_16x16x32_bf16 v[22:25], v[170:173], v[202:205], v[22:25]
	v_mfma_f32_16x16x32_bf16 v[18:21], v[178:181], v[202:205], v[18:21]
	v_mfma_f32_16x16x32_bf16 v[6:9], v[170:173], v[210:213], v[6:9]
	v_mfma_f32_16x16x32_bf16 v[2:5], v[178:181], v[210:213], v[2:5]
	v_mfma_f32_16x16x32_bf16 v[54:57], v[174:177], v[190:193], v[54:57]
	v_mfma_f32_16x16x32_bf16 v[50:53], v[182:185], v[190:193], v[50:53]
	v_mfma_f32_16x16x32_bf16 v[38:41], v[174:177], v[198:201], v[38:41]
	v_mfma_f32_16x16x32_bf16 v[34:37], v[182:185], v[198:201], v[34:37]
	v_mfma_f32_16x16x32_bf16 v[22:25], v[174:177], v[206:209], v[22:25]
	v_mfma_f32_16x16x32_bf16 v[18:21], v[182:185], v[206:209], v[18:21]
	v_mfma_f32_16x16x32_bf16 v[6:9], v[174:177], v[214:217], v[6:9]
	v_mfma_f32_16x16x32_bf16 v[2:5], v[182:185], v[214:217], v[2:5]
	s_barrier
	s_add_i32 s17, s17, 2
	s_add_u32 s84, s84, 0x100
	s_addc_u32 s85, s85, 0
	s_add_u32 s13, s13, 0x100
	s_addc_u32 s16, s16, 0
	s_cmp_gt_u32 s17, 61
	s_cbranch_scc0 .LBB0_541
	s_setprio 0
	s_and_b64 vcc, exec, s[42:43]
	s_cbranch_vccz .LBB0_544

.Lsp_p11:
.LBB0_1015:
	ds_read_b128 v[146:149], v156
	ds_read_b128 v[150:153], v156 offset:1024
	ds_read_b128 v[160:163], v156 offset:2048
	ds_read_b128 v[164:167], v156 offset:3072
	ds_read_b128 v[168:171], v157
	ds_read_b128 v[172:175], v157 offset:1024
	ds_read_b128 v[176:179], v157 offset:2048
	ds_read_b128 v[180:183], v157 offset:3072
	s_add_u32 s44, s42, 0xfff80080
	s_addc_u32 s45, s43, -1
	s_cmp_eq_u32 s67, 28
	s_cselect_b32 s47, s8, s45
	s_cselect_b32 s46, s9, s44
	s_cselect_b32 s45, s21, s66
	s_cselect_b32 s44, s23, s61
	v_lshl_add_u64 v[216:217], s[42:43], 0, v[138:139]
	s_add_i32 m0, s41, 0xc000
	ds_read_b128 v[184:187], v158
	ds_read_b128 v[188:191], v158 offset:1024
	ds_read_b128 v[192:195], v158 offset:2048
	ds_read_b128 v[196:199], v158 offset:3072
	ds_read_b128 v[200:203], v158 offset:4096
	ds_read_b128 v[204:207], v158 offset:5120
	ds_read_b128 v[208:211], v158 offset:6144
	ds_read_b128 v[212:215], v158 offset:7168
	global_load_lds_dwordx4 v[216:217], off
	v_lshl_add_u64 v[216:217], s[42:43], 0, v[140:141]
	s_add_i32 m0, s41, 0xe000
	s_nop 0
	global_load_lds_dwordx4 v[216:217], off
	s_waitcnt vmcnt(8)
	s_waitcnt lgkmcnt(0)
	s_barrier
	v_mfma_i32_16x16x64_i8 v[126:129], v[146:149], v[184:187], v[126:129]
	v_mfma_i32_16x16x64_i8 v[122:125], v[160:163], v[184:187], v[122:125]
	v_mfma_i32_16x16x64_i8 v[110:113], v[146:149], v[192:195], v[110:113]
	v_mfma_i32_16x16x64_i8 v[106:109], v[160:163], v[192:195], v[106:109]
	v_mfma_i32_16x16x64_i8 v[94:97], v[146:149], v[200:203], v[94:97]
	v_mfma_i32_16x16x64_i8 v[90:93], v[160:163], v[200:203], v[90:93]
	v_mfma_i32_16x16x64_i8 v[78:81], v[146:149], v[208:211], v[78:81]
	v_mfma_i32_16x16x64_i8 v[74:77], v[160:163], v[208:211], v[74:77]
	v_mfma_i32_16x16x64_i8 v[126:129], v[150:153], v[188:191], v[126:129]
	v_mfma_i32_16x16x64_i8 v[122:125], v[164:167], v[188:191], v[122:125]
	v_mfma_i32_16x16x64_i8 v[110:113], v[150:153], v[196:199], v[110:113]
	v_mfma_i32_16x16x64_i8 v[106:109], v[164:167], v[196:199], v[106:109]
	v_mfma_i32_16x16x64_i8 v[94:97], v[150:153], v[204:207], v[94:97]
	v_mfma_i32_16x16x64_i8 v[90:93], v[164:167], v[204:207], v[90:93]
	v_mfma_i32_16x16x64_i8 v[78:81], v[150:153], v[212:215], v[78:81]
	v_mfma_i32_16x16x64_i8 v[74:77], v[164:167], v[212:215], v[74:77]
	v_mfma_i32_16x16x64_i8 v[118:121], v[168:171], v[184:187], v[118:121]
	v_mfma_i32_16x16x64_i8 v[114:117], v[176:179], v[184:187], v[114:117]
	v_mfma_i32_16x16x64_i8 v[102:105], v[168:171], v[192:195], v[102:105]
	v_mfma_i32_16x16x64_i8 v[98:101], v[176:179], v[192:195], v[98:101]
	v_mfma_i32_16x16x64_i8 v[86:89], v[168:171], v[200:203], v[86:89]
	v_mfma_i32_16x16x64_i8 v[82:85], v[176:179], v[200:203], v[82:85]
	v_mfma_i32_16x16x64_i8 v[70:73], v[168:171], v[208:211], v[70:73]
	v_mfma_i32_16x16x64_i8 v[66:69], v[176:179], v[208:211], v[66:69]
	v_mfma_i32_16x16x64_i8 v[118:121], v[172:175], v[188:191], v[118:121]
	v_mfma_i32_16x16x64_i8 v[114:117], v[180:183], v[188:191], v[114:117]
	v_mfma_i32_16x16x64_i8 v[102:105], v[172:175], v[196:199], v[102:105]
	v_mfma_i32_16x16x64_i8 v[98:101], v[180:183], v[196:199], v[98:101]
	v_mfma_i32_16x16x64_i8 v[86:89], v[172:175], v[204:207], v[86:89]
	v_mfma_i32_16x16x64_i8 v[82:85], v[180:183], v[204:207], v[82:85]
	v_mfma_i32_16x16x64_i8 v[70:73], v[172:175], v[212:215], v[70:73]
	v_mfma_i32_16x16x64_i8 v[66:69], v[180:183], v[212:215], v[66:69]
	s_barrier
	s_add_i32 s68, s56, s19
	v_lshl_add_u64 v[216:217], s[44:45], 0, v[134:135]
	s_mov_b32 m0, s68
	ds_read_b128 v[184:187], v158 offset:16384
	ds_read_b128 v[188:191], v158 offset:17408
	ds_read_b128 v[192:195], v158 offset:18432
	ds_read_b128 v[196:199], v158 offset:19456
	ds_read_b128 v[200:203], v158 offset:20480
	ds_read_b128 v[204:207], v158 offset:21504
	ds_read_b128 v[208:211], v158 offset:22528
	ds_read_b128 v[212:215], v158 offset:23552
	global_load_lds_dwordx4 v[216:217], off
	s_add_i32 m0, s68, 0x2000
	s_add_u32 s68, s44, 0x80000
	v_lshl_add_u64 v[218:219], s[44:45], 0, v[130:131]
	s_addc_u32 s69, s45, 0
	s_add_i32 s72, s57, s19
	global_load_lds_dwordx4 v[218:219], off
	v_lshl_add_u64 v[220:221], s[68:69], 0, v[134:135]
	s_mov_b32 m0, s72
	v_lshl_add_u64 v[222:223], s[46:47], 0, v[132:133]
	global_load_lds_dwordx4 v[220:221], off
	v_lshl_add_u64 v[220:221], s[68:69], 0, v[130:131]
	s_add_i32 m0, s72, 0x2000
	s_nop 0
	global_load_lds_dwordx4 v[220:221], off
	v_lshl_add_u64 v[220:221], s[46:47], 0, v[136:137]
	s_mov_b32 m0, s41
	s_nop 0
	global_load_lds_dwordx4 v[220:221], off
	s_mov_b32 m0, s49
	s_nop 0
	global_load_lds_dwordx4 v[222:223], off
	s_waitcnt vmcnt(8)
	s_waitcnt lgkmcnt(0)
	s_barrier
	v_mfma_i32_16x16x64_i8 v[62:65], v[146:149], v[184:187], v[62:65]
	v_mfma_i32_16x16x64_i8 v[58:61], v[160:163], v[184:187], v[58:61]
	v_mfma_i32_16x16x64_i8 v[46:49], v[146:149], v[192:195], v[46:49]
	v_mfma_i32_16x16x64_i8 v[42:45], v[160:163], v[192:195], v[42:45]
	v_mfma_i32_16x16x64_i8 v[30:33], v[146:149], v[200:203], v[30:33]
	v_mfma_i32_16x16x64_i8 v[26:29], v[160:163], v[200:203], v[26:29]
	v_mfma_i32_16x16x64_i8 v[14:17], v[146:149], v[208:211], v[14:17]
	v_mfma_i32_16x16x64_i8 v[10:13], v[160:163], v[208:211], v[10:13]
	v_mfma_i32_16x16x64_i8 v[62:65], v[150:153], v[188:191], v[62:65]
	v_mfma_i32_16x16x64_i8 v[58:61], v[164:167], v[188:191], v[58:61]
	v_mfma_i32_16x16x64_i8 v[46:49], v[150:153], v[196:199], v[46:49]
	v_mfma_i32_16x16x64_i8 v[42:45], v[164:167], v[196:199], v[42:45]
	v_mfma_i32_16x16x64_i8 v[30:33], v[150:153], v[204:207], v[30:33]
	v_mfma_i32_16x16x64_i8 v[26:29], v[164:167], v[204:207], v[26:29]
	v_mfma_i32_16x16x64_i8 v[14:17], v[150:153], v[212:215], v[14:17]
	v_mfma_i32_16x16x64_i8 v[10:13], v[164:167], v[212:215], v[10:13]
	v_mfma_i32_16x16x64_i8 v[54:57], v[168:171], v[184:187], v[54:57]
	v_mfma_i32_16x16x64_i8 v[50:53], v[176:179], v[184:187], v[50:53]
	v_mfma_i32_16x16x64_i8 v[38:41], v[168:171], v[192:195], v[38:41]
	v_mfma_i32_16x16x64_i8 v[34:37], v[176:179], v[192:195], v[34:37]
	v_mfma_i32_16x16x64_i8 v[22:25], v[168:171], v[200:203], v[22:25]
	v_mfma_i32_16x16x64_i8 v[18:21], v[176:179], v[200:203], v[18:21]
	v_mfma_i32_16x16x64_i8 v[6:9], v[168:171], v[208:211], v[6:9]
	v_mfma_i32_16x16x64_i8 v[2:5], v[176:179], v[208:211], v[2:5]
	v_mfma_i32_16x16x64_i8 v[54:57], v[172:175], v[188:191], v[54:57]
	v_mfma_i32_16x16x64_i8 v[50:53], v[180:183], v[188:191], v[50:53]
	v_mfma_i32_16x16x64_i8 v[38:41], v[172:175], v[196:199], v[38:41]
	v_mfma_i32_16x16x64_i8 v[34:37], v[180:183], v[196:199], v[34:37]
	v_mfma_i32_16x16x64_i8 v[22:25], v[172:175], v[204:207], v[22:25]
	v_mfma_i32_16x16x64_i8 v[18:21], v[180:183], v[204:207], v[18:21]
	v_mfma_i32_16x16x64_i8 v[6:9], v[172:175], v[212:215], v[6:9]
	v_mfma_i32_16x16x64_i8 v[2:5], v[180:183], v[212:215], v[2:5]
	s_barrier
	s_add_i32 s68, 0, 0x18000
	v_add_u32_e32 v159, s68, v154
	s_add_i32 s69, 0, 0x1c000
	ds_read_b128 v[146:149], v159
	ds_read_b128 v[150:153], v159 offset:1024
	ds_read_b128 v[160:163], v159 offset:2048
	ds_read_b128 v[164:167], v159 offset:3072
	v_add_u32_e32 v159, s69, v154
	ds_read_b128 v[168:171], v159
	ds_read_b128 v[172:175], v159 offset:1024
	ds_read_b128 v[176:179], v159 offset:2048
	ds_read_b128 v[180:183], v159 offset:3072
	s_add_u32 s46, s46, 0x80000
	s_addc_u32 s47, s47, 0
	s_mov_b32 m0, s50
	v_lshl_add_u64 v[224:225], s[46:47], 0, v[136:137]
	ds_read_b128 v[184:187], v158 offset:32768
	ds_read_b128 v[188:191], v158 offset:33792
	ds_read_b128 v[192:195], v158 offset:34816
	ds_read_b128 v[196:199], v158 offset:35840
	ds_read_b128 v[200:203], v158 offset:36864
	ds_read_b128 v[204:207], v158 offset:37888
	ds_read_b128 v[208:211], v158 offset:38912
	ds_read_b128 v[212:215], v158 offset:39936
	global_load_lds_dwordx4 v[224:225], off
	v_lshl_add_u64 v[224:225], s[46:47], 0, v[132:133]
	s_mov_b32 m0, s51
	s_nop 0
	global_load_lds_dwordx4 v[224:225], off
	s_waitcnt vmcnt(8)
	s_waitcnt lgkmcnt(0)
	s_barrier
	v_mfma_i32_16x16x64_i8 v[126:129], v[146:149], v[184:187], v[126:129]
	v_mfma_i32_16x16x64_i8 v[122:125], v[160:163], v[184:187], v[122:125]
	v_mfma_i32_16x16x64_i8 v[110:113], v[146:149], v[192:195], v[110:113]
	v_mfma_i32_16x16x64_i8 v[106:109], v[160:163], v[192:195], v[106:109]
	v_mfma_i32_16x16x64_i8 v[94:97], v[146:149], v[200:203], v[94:97]
	v_mfma_i32_16x16x64_i8 v[90:93], v[160:163], v[200:203], v[90:93]
	v_mfma_i32_16x16x64_i8 v[78:81], v[146:149], v[208:211], v[78:81]
	v_mfma_i32_16x16x64_i8 v[74:77], v[160:163], v[208:211], v[74:77]
	v_mfma_i32_16x16x64_i8 v[126:129], v[150:153], v[188:191], v[126:129]
	v_mfma_i32_16x16x64_i8 v[122:125], v[164:167], v[188:191], v[122:125]
	v_mfma_i32_16x16x64_i8 v[110:113], v[150:153], v[196:199], v[110:113]
	v_mfma_i32_16x16x64_i8 v[106:109], v[164:167], v[196:199], v[106:109]
	v_mfma_i32_16x16x64_i8 v[94:97], v[150:153], v[204:207], v[94:97]
	v_mfma_i32_16x16x64_i8 v[90:93], v[164:167], v[204:207], v[90:93]
	v_mfma_i32_16x16x64_i8 v[78:81], v[150:153], v[212:215], v[78:81]
	v_mfma_i32_16x16x64_i8 v[74:77], v[164:167], v[212:215], v[74:77]
	v_mfma_i32_16x16x64_i8 v[118:121], v[168:171], v[184:187], v[118:121]
	v_mfma_i32_16x16x64_i8 v[114:117], v[176:179], v[184:187], v[114:117]
	v_mfma_i32_16x16x64_i8 v[102:105], v[168:171], v[192:195], v[102:105]
	v_mfma_i32_16x16x64_i8 v[98:101], v[176:179], v[192:195], v[98:101]
	v_mfma_i32_16x16x64_i8 v[86:89], v[168:171], v[200:203], v[86:89]
	v_mfma_i32_16x16x64_i8 v[82:85], v[176:179], v[200:203], v[82:85]
	v_mfma_i32_16x16x64_i8 v[70:73], v[168:171], v[208:211], v[70:73]
	v_mfma_i32_16x16x64_i8 v[66:69], v[176:179], v[208:211], v[66:69]
	v_mfma_i32_16x16x64_i8 v[118:121], v[172:175], v[188:191], v[118:121]
	v_mfma_i32_16x16x64_i8 v[114:117], v[180:183], v[188:191], v[114:117]
	v_mfma_i32_16x16x64_i8 v[102:105], v[172:175], v[196:199], v[102:105]
	v_mfma_i32_16x16x64_i8 v[98:101], v[180:183], v[196:199], v[98:101]
	v_mfma_i32_16x16x64_i8 v[86:89], v[172:175], v[204:207], v[86:89]
	v_mfma_i32_16x16x64_i8 v[82:85], v[180:183], v[204:207], v[82:85]
	v_mfma_i32_16x16x64_i8 v[70:73], v[172:175], v[212:215], v[70:73]
	v_mfma_i32_16x16x64_i8 v[66:69], v[180:183], v[212:215], v[66:69]
	s_barrier
	s_add_i32 s46, s68, s19
	v_lshl_add_u64 v[216:217], v[216:217], 0, s[4:5]
	s_mov_b32 m0, s46
	ds_read_b128 v[184:187], v158 offset:49152
	ds_read_b128 v[188:191], v158 offset:50176
	ds_read_b128 v[192:195], v158 offset:51200
	ds_read_b128 v[196:199], v158 offset:52224
	ds_read_b128 v[200:203], v158 offset:53248
	ds_read_b128 v[204:207], v158 offset:54272
	ds_read_b128 v[208:211], v158 offset:55296
	ds_read_b128 v[212:215], v158 offset:56320
	global_load_lds_dwordx4 v[216:217], off
	s_add_i32 m0, s46, 0x2000
	s_add_u32 s44, s44, 0x80080
	v_lshl_add_u64 v[216:217], v[218:219], 0, s[4:5]
	s_addc_u32 s45, s45, 0
	s_add_i32 s46, s69, s19
	global_load_lds_dwordx4 v[216:217], off
	v_lshl_add_u64 v[216:217], s[44:45], 0, v[134:135]
	s_mov_b32 m0, s46
	s_nop 0
	global_load_lds_dwordx4 v[216:217], off
	v_lshl_add_u64 v[216:217], s[44:45], 0, v[130:131]
	s_add_i32 m0, s46, 0x2000
	s_nop 0
	global_load_lds_dwordx4 v[216:217], off
	v_lshl_add_u64 v[216:217], v[220:221], 0, s[4:5]
	s_mov_b32 m0, s53
	s_nop 0
	global_load_lds_dwordx4 v[216:217], off
	v_lshl_add_u64 v[216:217], v[222:223], 0, s[4:5]
	s_mov_b32 m0, s54
	s_nop 0
	global_load_lds_dwordx4 v[216:217], off
	s_waitcnt vmcnt(8)
	s_waitcnt lgkmcnt(0)
	s_barrier
	v_mfma_i32_16x16x64_i8 v[62:65], v[146:149], v[184:187], v[62:65]
	v_mfma_i32_16x16x64_i8 v[58:61], v[160:163], v[184:187], v[58:61]
	v_mfma_i32_16x16x64_i8 v[46:49], v[146:149], v[192:195], v[46:49]
	v_mfma_i32_16x16x64_i8 v[42:45], v[160:163], v[192:195], v[42:45]
	v_mfma_i32_16x16x64_i8 v[30:33], v[146:149], v[200:203], v[30:33]
	v_mfma_i32_16x16x64_i8 v[26:29], v[160:163], v[200:203], v[26:29]
	v_mfma_i32_16x16x64_i8 v[14:17], v[146:149], v[208:211], v[14:17]
	v_mfma_i32_16x16x64_i8 v[10:13], v[160:163], v[208:211], v[10:13]
	v_mfma_i32_16x16x64_i8 v[62:65], v[150:153], v[188:191], v[62:65]
	v_mfma_i32_16x16x64_i8 v[58:61], v[164:167], v[188:191], v[58:61]
	v_mfma_i32_16x16x64_i8 v[46:49], v[150:153], v[196:199], v[46:49]
	v_mfma_i32_16x16x64_i8 v[42:45], v[164:167], v[196:199], v[42:45]
	v_mfma_i32_16x16x64_i8 v[30:33], v[150:153], v[204:207], v[30:33]
	v_mfma_i32_16x16x64_i8 v[26:29], v[164:167], v[204:207], v[26:29]
	v_mfma_i32_16x16x64_i8 v[14:17], v[150:153], v[212:215], v[14:17]
	v_mfma_i32_16x16x64_i8 v[10:13], v[164:167], v[212:215], v[10:13]
	v_mfma_i32_16x16x64_i8 v[54:57], v[168:171], v[184:187], v[54:57]
	v_mfma_i32_16x16x64_i8 v[50:53], v[176:179], v[184:187], v[50:53]
	v_mfma_i32_16x16x64_i8 v[38:41], v[168:171], v[192:195], v[38:41]
	v_mfma_i32_16x16x64_i8 v[34:37], v[176:179], v[192:195], v[34:37]
	v_mfma_i32_16x16x64_i8 v[22:25], v[168:171], v[200:203], v[22:25]
	v_mfma_i32_16x16x64_i8 v[18:21], v[176:179], v[200:203], v[18:21]
	v_mfma_i32_16x16x64_i8 v[6:9], v[168:171], v[208:211], v[6:9]
	v_mfma_i32_16x16x64_i8 v[2:5], v[176:179], v[208:211], v[2:5]
	v_mfma_i32_16x16x64_i8 v[54:57], v[172:175], v[188:191], v[54:57]
	v_mfma_i32_16x16x64_i8 v[50:53], v[180:183], v[188:191], v[50:53]
	v_mfma_i32_16x16x64_i8 v[38:41], v[172:175], v[196:199], v[38:41]
	v_mfma_i32_16x16x64_i8 v[34:37], v[180:183], v[196:199], v[34:37]
	v_mfma_i32_16x16x64_i8 v[22:25], v[172:175], v[204:207], v[22:25]
	v_mfma_i32_16x16x64_i8 v[18:21], v[180:183], v[204:207], v[18:21]
	v_mfma_i32_16x16x64_i8 v[6:9], v[172:175], v[212:215], v[6:9]
	v_mfma_i32_16x16x64_i8 v[2:5], v[180:183], v[212:215], v[2:5]
	s_barrier
	s_add_i32 s67, s67, 2
	s_add_u32 s42, s42, 0x100
	s_addc_u32 s43, s43, 0
	s_add_u32 s61, s61, 0x100
	s_addc_u32 s66, s66, 0
	s_cmp_gt_u32 s67, 29
	s_cbranch_scc0 .LBB0_1015
	s_setprio 0
	s_and_b64 vcc, exec, s[12:13]
	s_cbranch_vccz .LBB0_1018

.Lsp_p13:
.LBB0_1166:
	ds_read_b128 v[104:107], v167
	ds_read_b128 v[108:111], v167 offset:1024
	ds_read_b128 v[112:115], v167 offset:2048
	ds_read_b128 v[120:123], v167 offset:3072
	ds_read_b128 v[158:161], v168
	ds_read_b128 v[170:173], v168 offset:1024
	ds_read_b128 v[174:177], v168 offset:2048
	ds_read_b128 v[178:181], v168 offset:3072
	s_add_u32 s26, s6, 0xffea8080
	s_addc_u32 s27, s7, -1
	s_cmpk_eq_i32 s55, 0x52
	s_cselect_b32 s29, s23, s27
	s_cselect_b32 s28, s22, s26
	s_cselect_b32 s27, s25, s9
	s_cselect_b32 s26, s24, s8
	v_lshl_add_u64 v[214:215], s[6:7], 0, v[152:153]
	s_add_i32 m0, s38, 0xc000
	ds_read_b128 v[182:185], v169
	ds_read_b128 v[186:189], v169 offset:1024
	ds_read_b128 v[190:193], v169 offset:2048
	ds_read_b128 v[194:197], v169 offset:3072
	ds_read_b128 v[198:201], v169 offset:4096
	ds_read_b128 v[202:205], v169 offset:5120
	ds_read_b128 v[206:209], v169 offset:6144
	ds_read_b128 v[210:213], v169 offset:7168
	global_load_lds_dwordx4 v[214:215], off
	v_lshl_add_u64 v[214:215], s[6:7], 0, v[154:155]
	s_add_i32 m0, s38, 0xe000
	s_nop 0
	global_load_lds_dwordx4 v[214:215], off
	s_waitcnt vmcnt(8)
	s_waitcnt lgkmcnt(0)
	s_barrier
	v_mfma_i32_16x16x64_i8 v[140:143], v[104:107], v[182:185], v[140:143]
	v_mfma_i32_16x16x64_i8 v[136:139], v[112:115], v[182:185], v[136:139]
	v_mfma_i32_16x16x64_i8 v[124:127], v[104:107], v[190:193], v[124:127]
	v_mfma_i32_16x16x64_i8 v[116:119], v[112:115], v[190:193], v[116:119]
	v_mfma_i32_16x16x64_i8 v[92:95], v[104:107], v[198:201], v[92:95]
	v_mfma_i32_16x16x64_i8 v[88:91], v[112:115], v[198:201], v[88:91]
	v_mfma_i32_16x16x64_i8 v[76:79], v[104:107], v[206:209], v[76:79]
	v_mfma_i32_16x16x64_i8 v[72:75], v[112:115], v[206:209], v[72:75]
	v_mfma_i32_16x16x64_i8 v[140:143], v[108:111], v[186:189], v[140:143]
	v_mfma_i32_16x16x64_i8 v[136:139], v[120:123], v[186:189], v[136:139]
	v_mfma_i32_16x16x64_i8 v[124:127], v[108:111], v[194:197], v[124:127]
	v_mfma_i32_16x16x64_i8 v[116:119], v[120:123], v[194:197], v[116:119]
	v_mfma_i32_16x16x64_i8 v[92:95], v[108:111], v[202:205], v[92:95]
	v_mfma_i32_16x16x64_i8 v[88:91], v[120:123], v[202:205], v[88:91]
	v_mfma_i32_16x16x64_i8 v[76:79], v[108:111], v[210:213], v[76:79]
	v_mfma_i32_16x16x64_i8 v[72:75], v[120:123], v[210:213], v[72:75]
	v_mfma_i32_16x16x64_i8 v[132:135], v[158:161], v[182:185], v[132:135]
	v_mfma_i32_16x16x64_i8 v[128:131], v[174:177], v[182:185], v[128:131]
	v_mfma_i32_16x16x64_i8 v[100:103], v[158:161], v[190:193], v[100:103]
	v_mfma_i32_16x16x64_i8 v[96:99], v[174:177], v[190:193], v[96:99]
	v_mfma_i32_16x16x64_i8 v[84:87], v[158:161], v[198:201], v[84:87]
	v_mfma_i32_16x16x64_i8 v[80:83], v[174:177], v[198:201], v[80:83]
	v_mfma_i32_16x16x64_i8 v[68:71], v[158:161], v[206:209], v[68:71]
	v_mfma_i32_16x16x64_i8 v[64:67], v[174:177], v[206:209], v[64:67]
	v_mfma_i32_16x16x64_i8 v[132:135], v[170:173], v[186:189], v[132:135]
	v_mfma_i32_16x16x64_i8 v[128:131], v[178:181], v[186:189], v[128:131]
	v_mfma_i32_16x16x64_i8 v[100:103], v[170:173], v[194:197], v[100:103]
	v_mfma_i32_16x16x64_i8 v[96:99], v[178:181], v[194:197], v[96:99]
	v_mfma_i32_16x16x64_i8 v[84:87], v[170:173], v[202:205], v[84:87]
	v_mfma_i32_16x16x64_i8 v[80:83], v[178:181], v[202:205], v[80:83]
	v_mfma_i32_16x16x64_i8 v[68:71], v[170:173], v[210:213], v[68:71]
	v_mfma_i32_16x16x64_i8 v[64:67], v[178:181], v[210:213], v[64:67]
	s_barrier
	s_add_i32 s56, s48, s35
	v_lshl_add_u64 v[214:215], s[26:27], 0, v[146:147]
	s_mov_b32 m0, s56
	ds_read_b128 v[182:185], v169 offset:16384
	ds_read_b128 v[186:189], v169 offset:17408
	ds_read_b128 v[190:193], v169 offset:18432
	ds_read_b128 v[194:197], v169 offset:19456
	ds_read_b128 v[198:201], v169 offset:20480
	ds_read_b128 v[202:205], v169 offset:21504
	ds_read_b128 v[206:209], v169 offset:22528
	ds_read_b128 v[210:213], v169 offset:23552
	global_load_lds_dwordx4 v[214:215], off
	s_add_i32 m0, s56, 0x2000
	s_add_u32 s56, s26, 0x158000
	v_lshl_add_u64 v[216:217], s[26:27], 0, v[150:151]
	s_addc_u32 s57, s27, 0
	s_add_i32 s58, s49, s35
	global_load_lds_dwordx4 v[216:217], off
	v_lshl_add_u64 v[218:219], s[56:57], 0, v[146:147]
	s_mov_b32 m0, s58
	v_lshl_add_u64 v[220:221], s[28:29], 0, v[148:149]
	global_load_lds_dwordx4 v[218:219], off
	v_lshl_add_u64 v[218:219], s[56:57], 0, v[150:151]
	s_add_i32 m0, s58, 0x2000
	s_nop 0
	global_load_lds_dwordx4 v[218:219], off
	v_lshl_add_u64 v[218:219], s[28:29], 0, v[144:145]
	s_mov_b32 m0, s38
	s_nop 0
	global_load_lds_dwordx4 v[218:219], off
	s_mov_b32 m0, s39
	s_nop 0
	global_load_lds_dwordx4 v[220:221], off
	s_waitcnt vmcnt(8)
	s_waitcnt lgkmcnt(0)
	s_barrier
	v_mfma_i32_16x16x64_i8 v[60:63], v[104:107], v[182:185], v[60:63]
	v_mfma_i32_16x16x64_i8 v[56:59], v[112:115], v[182:185], v[56:59]
	v_mfma_i32_16x16x64_i8 v[44:47], v[104:107], v[190:193], v[44:47]
	v_mfma_i32_16x16x64_i8 v[40:43], v[112:115], v[190:193], v[40:43]
	v_mfma_i32_16x16x64_i8 v[28:31], v[104:107], v[198:201], v[28:31]
	v_mfma_i32_16x16x64_i8 v[24:27], v[112:115], v[198:201], v[24:27]
	v_mfma_i32_16x16x64_i8 v[12:15], v[104:107], v[206:209], v[12:15]
	v_mfma_i32_16x16x64_i8 v[8:11], v[112:115], v[206:209], v[8:11]
	v_mfma_i32_16x16x64_i8 v[60:63], v[108:111], v[186:189], v[60:63]
	v_mfma_i32_16x16x64_i8 v[56:59], v[120:123], v[186:189], v[56:59]
	v_mfma_i32_16x16x64_i8 v[44:47], v[108:111], v[194:197], v[44:47]
	v_mfma_i32_16x16x64_i8 v[40:43], v[120:123], v[194:197], v[40:43]
	v_mfma_i32_16x16x64_i8 v[28:31], v[108:111], v[202:205], v[28:31]
	v_mfma_i32_16x16x64_i8 v[24:27], v[120:123], v[202:205], v[24:27]
	v_mfma_i32_16x16x64_i8 v[12:15], v[108:111], v[210:213], v[12:15]
	v_mfma_i32_16x16x64_i8 v[8:11], v[120:123], v[210:213], v[8:11]
	v_mfma_i32_16x16x64_i8 v[52:55], v[158:161], v[182:185], v[52:55]
	v_mfma_i32_16x16x64_i8 v[48:51], v[174:177], v[182:185], v[48:51]
	v_mfma_i32_16x16x64_i8 v[36:39], v[158:161], v[190:193], v[36:39]
	v_mfma_i32_16x16x64_i8 v[32:35], v[174:177], v[190:193], v[32:35]
	v_mfma_i32_16x16x64_i8 v[20:23], v[158:161], v[198:201], v[20:23]
	v_mfma_i32_16x16x64_i8 v[16:19], v[174:177], v[198:201], v[16:19]
	v_mfma_i32_16x16x64_i8 v[4:7], v[158:161], v[206:209], v[4:7]
	v_mfma_i32_16x16x64_i8 v[0:3], v[174:177], v[206:209], v[0:3]
	v_mfma_i32_16x16x64_i8 v[52:55], v[170:173], v[186:189], v[52:55]
	v_mfma_i32_16x16x64_i8 v[48:51], v[178:181], v[186:189], v[48:51]
	v_mfma_i32_16x16x64_i8 v[36:39], v[170:173], v[194:197], v[36:39]
	v_mfma_i32_16x16x64_i8 v[32:35], v[178:181], v[194:197], v[32:35]
	v_mfma_i32_16x16x64_i8 v[20:23], v[170:173], v[202:205], v[20:23]
	v_mfma_i32_16x16x64_i8 v[16:19], v[178:181], v[202:205], v[16:19]
	v_mfma_i32_16x16x64_i8 v[4:7], v[170:173], v[210:213], v[4:7]
	v_mfma_i32_16x16x64_i8 v[0:3], v[178:181], v[210:213], v[0:3]
	s_barrier
	s_add_i32 s56, 0, 0x18000
	s_add_i32 s57, 0, 0x1c000
	v_add_u32_e32 v120, s56, v165
	v_add_u32_e32 v162, s57, v165
	ds_read_b128 v[104:107], v120
	ds_read_b128 v[108:111], v120 offset:1024
	ds_read_b128 v[112:115], v120 offset:2048
	ds_read_b128 v[120:123], v120 offset:3072
	ds_read_b128 v[158:161], v162
	ds_read_b128 v[170:173], v162 offset:1024
	ds_read_b128 v[174:177], v162 offset:2048
	ds_read_b128 v[178:181], v162 offset:3072
	s_add_u32 s28, s28, 0x158000
	s_addc_u32 s29, s29, 0
	s_mov_b32 m0, s40
	v_lshl_add_u64 v[222:223], s[28:29], 0, v[144:145]
	ds_read_b128 v[182:185], v169 offset:32768
	ds_read_b128 v[186:189], v169 offset:33792
	ds_read_b128 v[190:193], v169 offset:34816
	ds_read_b128 v[194:197], v169 offset:35840
	ds_read_b128 v[198:201], v169 offset:36864
	ds_read_b128 v[202:205], v169 offset:37888
	ds_read_b128 v[206:209], v169 offset:38912
	ds_read_b128 v[210:213], v169 offset:39936
	global_load_lds_dwordx4 v[222:223], off
	v_lshl_add_u64 v[222:223], s[28:29], 0, v[148:149]
	s_mov_b32 m0, s41
	s_nop 0
	global_load_lds_dwordx4 v[222:223], off
	s_waitcnt vmcnt(8)
	s_waitcnt lgkmcnt(0)
	s_barrier
	v_mfma_i32_16x16x64_i8 v[140:143], v[104:107], v[182:185], v[140:143]
	v_mfma_i32_16x16x64_i8 v[136:139], v[112:115], v[182:185], v[136:139]
	v_mfma_i32_16x16x64_i8 v[124:127], v[104:107], v[190:193], v[124:127]
	v_mfma_i32_16x16x64_i8 v[116:119], v[112:115], v[190:193], v[116:119]
	v_mfma_i32_16x16x64_i8 v[92:95], v[104:107], v[198:201], v[92:95]
	v_mfma_i32_16x16x64_i8 v[88:91], v[112:115], v[198:201], v[88:91]
	v_mfma_i32_16x16x64_i8 v[76:79], v[104:107], v[206:209], v[76:79]
	v_mfma_i32_16x16x64_i8 v[72:75], v[112:115], v[206:209], v[72:75]
	v_mfma_i32_16x16x64_i8 v[140:143], v[108:111], v[186:189], v[140:143]
	v_mfma_i32_16x16x64_i8 v[136:139], v[120:123], v[186:189], v[136:139]
	v_mfma_i32_16x16x64_i8 v[124:127], v[108:111], v[194:197], v[124:127]
	v_mfma_i32_16x16x64_i8 v[116:119], v[120:123], v[194:197], v[116:119]
	v_mfma_i32_16x16x64_i8 v[92:95], v[108:111], v[202:205], v[92:95]
	v_mfma_i32_16x16x64_i8 v[88:91], v[120:123], v[202:205], v[88:91]
	v_mfma_i32_16x16x64_i8 v[76:79], v[108:111], v[210:213], v[76:79]
	v_mfma_i32_16x16x64_i8 v[72:75], v[120:123], v[210:213], v[72:75]
	v_mfma_i32_16x16x64_i8 v[132:135], v[158:161], v[182:185], v[132:135]
	v_mfma_i32_16x16x64_i8 v[128:131], v[174:177], v[182:185], v[128:131]
	v_mfma_i32_16x16x64_i8 v[100:103], v[158:161], v[190:193], v[100:103]
	v_mfma_i32_16x16x64_i8 v[96:99], v[174:177], v[190:193], v[96:99]
	v_mfma_i32_16x16x64_i8 v[84:87], v[158:161], v[198:201], v[84:87]
	v_mfma_i32_16x16x64_i8 v[80:83], v[174:177], v[198:201], v[80:83]
	v_mfma_i32_16x16x64_i8 v[68:71], v[158:161], v[206:209], v[68:71]
	v_mfma_i32_16x16x64_i8 v[64:67], v[174:177], v[206:209], v[64:67]
	v_mfma_i32_16x16x64_i8 v[132:135], v[170:173], v[186:189], v[132:135]
	v_mfma_i32_16x16x64_i8 v[128:131], v[178:181], v[186:189], v[128:131]
	v_mfma_i32_16x16x64_i8 v[100:103], v[170:173], v[194:197], v[100:103]
	v_mfma_i32_16x16x64_i8 v[96:99], v[178:181], v[194:197], v[96:99]
	v_mfma_i32_16x16x64_i8 v[84:87], v[170:173], v[202:205], v[84:87]
	v_mfma_i32_16x16x64_i8 v[80:83], v[178:181], v[202:205], v[80:83]
	v_mfma_i32_16x16x64_i8 v[68:71], v[170:173], v[210:213], v[68:71]
	v_mfma_i32_16x16x64_i8 v[64:67], v[178:181], v[210:213], v[64:67]
	s_barrier
	s_add_i32 s28, s56, s35
	v_lshl_add_u64 v[214:215], v[214:215], 0, s[16:17]
	s_mov_b32 m0, s28
	ds_read_b128 v[182:185], v169 offset:49152
	ds_read_b128 v[186:189], v169 offset:50176
	ds_read_b128 v[190:193], v169 offset:51200
	ds_read_b128 v[194:197], v169 offset:52224
	ds_read_b128 v[198:201], v169 offset:53248
	ds_read_b128 v[202:205], v169 offset:54272
	ds_read_b128 v[206:209], v169 offset:55296
	ds_read_b128 v[210:213], v169 offset:56320
	global_load_lds_dwordx4 v[214:215], off
	s_add_i32 m0, s28, 0x2000
	s_add_u32 s26, s26, 0x158080
	v_lshl_add_u64 v[214:215], v[216:217], 0, s[16:17]
	s_addc_u32 s27, s27, 0
	s_add_i32 s28, s57, s35
	global_load_lds_dwordx4 v[214:215], off
	v_lshl_add_u64 v[214:215], s[26:27], 0, v[146:147]
	s_mov_b32 m0, s28
	s_nop 0
	global_load_lds_dwordx4 v[214:215], off
	v_lshl_add_u64 v[214:215], s[26:27], 0, v[150:151]
	s_add_i32 m0, s28, 0x2000
	s_nop 0
	global_load_lds_dwordx4 v[214:215], off
	v_lshl_add_u64 v[214:215], v[218:219], 0, s[16:17]
	s_mov_b32 m0, s42
	s_nop 0
	global_load_lds_dwordx4 v[214:215], off
	v_lshl_add_u64 v[214:215], v[220:221], 0, s[16:17]
	s_mov_b32 m0, s43
	s_nop 0
	global_load_lds_dwordx4 v[214:215], off
	s_waitcnt vmcnt(8)
	s_waitcnt lgkmcnt(0)
	s_barrier
	v_mfma_i32_16x16x64_i8 v[60:63], v[104:107], v[182:185], v[60:63]
	v_mfma_i32_16x16x64_i8 v[56:59], v[112:115], v[182:185], v[56:59]
	v_mfma_i32_16x16x64_i8 v[44:47], v[104:107], v[190:193], v[44:47]
	v_mfma_i32_16x16x64_i8 v[40:43], v[112:115], v[190:193], v[40:43]
	v_mfma_i32_16x16x64_i8 v[28:31], v[104:107], v[198:201], v[28:31]
	v_mfma_i32_16x16x64_i8 v[24:27], v[112:115], v[198:201], v[24:27]
	v_mfma_i32_16x16x64_i8 v[12:15], v[104:107], v[206:209], v[12:15]
	v_mfma_i32_16x16x64_i8 v[8:11], v[112:115], v[206:209], v[8:11]
	v_mfma_i32_16x16x64_i8 v[60:63], v[108:111], v[186:189], v[60:63]
	v_mfma_i32_16x16x64_i8 v[56:59], v[120:123], v[186:189], v[56:59]
	v_mfma_i32_16x16x64_i8 v[44:47], v[108:111], v[194:197], v[44:47]
	v_mfma_i32_16x16x64_i8 v[40:43], v[120:123], v[194:197], v[40:43]
	v_mfma_i32_16x16x64_i8 v[28:31], v[108:111], v[202:205], v[28:31]
	v_mfma_i32_16x16x64_i8 v[24:27], v[120:123], v[202:205], v[24:27]
	v_mfma_i32_16x16x64_i8 v[12:15], v[108:111], v[210:213], v[12:15]
	v_mfma_i32_16x16x64_i8 v[8:11], v[120:123], v[210:213], v[8:11]
	v_mfma_i32_16x16x64_i8 v[52:55], v[158:161], v[182:185], v[52:55]
	v_mfma_i32_16x16x64_i8 v[48:51], v[174:177], v[182:185], v[48:51]
	v_mfma_i32_16x16x64_i8 v[36:39], v[158:161], v[190:193], v[36:39]
	v_mfma_i32_16x16x64_i8 v[32:35], v[174:177], v[190:193], v[32:35]
	v_mfma_i32_16x16x64_i8 v[20:23], v[158:161], v[198:201], v[20:23]
	v_mfma_i32_16x16x64_i8 v[16:19], v[174:177], v[198:201], v[16:19]
	v_mfma_i32_16x16x64_i8 v[4:7], v[158:161], v[206:209], v[4:7]
	v_mfma_i32_16x16x64_i8 v[0:3], v[174:177], v[206:209], v[0:3]
	v_mfma_i32_16x16x64_i8 v[52:55], v[170:173], v[186:189], v[52:55]
	v_mfma_i32_16x16x64_i8 v[48:51], v[178:181], v[186:189], v[48:51]
	v_mfma_i32_16x16x64_i8 v[36:39], v[170:173], v[194:197], v[36:39]
	v_mfma_i32_16x16x64_i8 v[32:35], v[178:181], v[194:197], v[32:35]
	v_mfma_i32_16x16x64_i8 v[20:23], v[170:173], v[202:205], v[20:23]
	v_mfma_i32_16x16x64_i8 v[16:19], v[178:181], v[202:205], v[16:19]
	v_mfma_i32_16x16x64_i8 v[4:7], v[170:173], v[210:213], v[4:7]
	v_mfma_i32_16x16x64_i8 v[0:3], v[178:181], v[210:213], v[0:3]
	s_barrier
	s_add_i32 s55, s55, 2
	s_add_u32 s6, s6, 0x100
	s_addc_u32 s7, s7, 0
	s_add_u32 s8, s8, 0x100
	s_addc_u32 s9, s9, 0
	s_cmpk_gt_u32 s55, 0x53
	s_cbranch_scc0 .LBB0_1166
	s_setprio 0
	s_and_b64 vcc, exec, s[18:19]
	s_cbranch_vccz .LBB0_1169
